# attention row sums on f32 VALU instead of ones-MFMA; p1 init via srcC; E2 gain loads hoisted
# speedup vs baseline: 1.0138x; 1.0138x over previous
; #define SBAR() __builtin_amdgcn_sched_barrier(0)
; __device__ __forceinline__ void partialSM2(f32x16& p0, f32x16& p1, float& m_hat, f32x16& negm, float& alpha) {
;     float pmax = fmaxf(p0[0], p0[1]);
; #pragma unroll
;     for (int r = 2; r < 16; ++r) pmax = fmaxf(pmax, p0[r]);
; #pragma unroll
;     for (int r = 0; r < 16; ++r) pmax = fmaxf(pmax, p1[r]);
;     { auto rr = __builtin_amdgcn_permlane32_swap(__float_as_uint(pmax), __float_as_uint(pmax), false, false);
;       pmax = fmaxf(__uint_as_float(rr[0]), __uint_as_float(rr[1])); }
;     if (__builtin_expect(__all(pmax <= THR2), 1)) { alpha = 1.f; }
; template <int DQK> __device__ __forceinline__ void qkt(f32x16& p0, f32x16& p1, const char* Ks, const bf16x8* qr, const char* qrl, int r32, int hi, const f32x16& c0) {
;     constexpr int ROWB = Cfg<DQK>::ROWB;
;     p0 = c0; p1 = c0;
; #pragma unroll
;     for (int d0 = 0; d0 < 8; ++d0) { const int cb = (d0 * 16 + hi * 8) * 2;
;         bf16x8 b0 = *reinterpret_cast<const bf16x8*>(Ks + r32 * ROWB + (cb ^ kswz<DQK>(r32)));
;         bf16x8 b1 = *reinterpret_cast<const bf16x8*>(Ks + (32 + r32) * ROWB + (cb ^ kswz<DQK>(r32)));
;         p0 = __builtin_amdgcn_mfma_f32_32x32x16_bf16(b0, qr[d0], p0, 0, 0, 0);
;         p1 = __builtin_amdgcn_mfma_f32_32x32x16_bf16(b1, qr[d0], p1, 0, 0, 0);
;         if constexpr (DQK == 192) { if (d0 == 3 || d0 == 7) SBAR(); } }
;     if constexpr (DQK == 192) {
; #pragma unroll
;         for (int d0 = 8; d0 < 12; ++d0) { const int cb = (d0 * 16 + hi * 8) * 2;
;             const bf16x8 q = *reinterpret_cast<const bf16x8*>(qrl + (d0 - 8) * 1024);
;             bf16x8 b0 = *reinterpret_cast<const bf16x8*>(Ks + r32 * ROWB + (cb ^ kswz<DQK>(r32)));
;             bf16x8 b1 = *reinterpret_cast<const bf16x8*>(Ks + (32 + r32) * ROWB + (cb ^ kswz<DQK>(r32)));
;             p0 = __builtin_amdgcn_mfma_f32_32x32x16_bf16(b0, q, p0, 0, 0, 0);
;             p1 = __builtin_amdgcn_mfma_f32_32x32x16_bf16(b1, q, p1, 0, 0, 0); }
;     }
; }
.LBB0_100:
	s_mov_b32 s9, s4
	s_mov_b32 s4, s11
	s_and_b32 s15, s14, 1
	s_mul_i32 s11, s15, 0x6000
	v_add_u32_e32 v0, s11, v234
	v_add_u32_e32 v6, v0, v235
	ds_read_b128 v[2:5], v6 offset:49152
	s_waitcnt vmcnt(12) lgkmcnt(0)
	v_mfma_f32_32x32x16_bf16 v[128:143], v[2:5], v[144:147], v[96:111]
	ds_read_b128 v[2:5], v6 offset:61440
	v_add_u32_e32 v6, v0, v236
	s_waitcnt lgkmcnt(0)
	v_mfma_f32_32x32x16_bf16 v[112:127], v[2:5], v[144:147], v[96:111]
	ds_read_b128 v[2:5], v6 offset:49152
	s_waitcnt vmcnt(11) lgkmcnt(0)
	v_mfma_f32_32x32x16_bf16 v[128:143], v[2:5], v[148:151], v[128:143]
	ds_read_b128 v[2:5], v6 offset:61440
	v_add_u32_e32 v6, v0, v237
	s_waitcnt lgkmcnt(0)
	v_mfma_f32_32x32x16_bf16 v[112:127], v[2:5], v[148:151], v[112:127]
	ds_read_b128 v[2:5], v6 offset:49152
	s_waitcnt vmcnt(10) lgkmcnt(0)
	v_mfma_f32_32x32x16_bf16 v[128:143], v[2:5], v[152:155], v[128:143]
	ds_read_b128 v[2:5], v6 offset:61440
	v_add_u32_e32 v6, v0, v238
	s_waitcnt lgkmcnt(0)
	v_mfma_f32_32x32x16_bf16 v[112:127], v[2:5], v[152:155], v[112:127]
	ds_read_b128 v[2:5], v6 offset:49152
	s_waitcnt vmcnt(9) lgkmcnt(0)
	v_mfma_f32_32x32x16_bf16 v[128:143], v[2:5], v[156:159], v[128:143]
	ds_read_b128 v[2:5], v6 offset:61440
	s_waitcnt lgkmcnt(0)
	v_mfma_f32_32x32x16_bf16 v[112:127], v[2:5], v[156:159], v[112:127]
	v_add_u32_e32 v6, v0, v239
	ds_read_b128 v[2:5], v6 offset:49152
	s_waitcnt vmcnt(8) lgkmcnt(0)
	v_mfma_f32_32x32x16_bf16 v[128:143], v[2:5], v[160:163], v[128:143]
	ds_read_b128 v[2:5], v6 offset:61440
	v_add_u32_e32 v6, v0, v240
	s_waitcnt lgkmcnt(0)
	v_mfma_f32_32x32x16_bf16 v[112:127], v[2:5], v[160:163], v[112:127]
	ds_read_b128 v[2:5], v6 offset:49152
	s_waitcnt vmcnt(7) lgkmcnt(0)
	v_mfma_f32_32x32x16_bf16 v[128:143], v[2:5], v[164:167], v[128:143]
	ds_read_b128 v[2:5], v6 offset:61440
	v_add_u32_e32 v6, v0, v241
	s_waitcnt lgkmcnt(0)
	v_mfma_f32_32x32x16_bf16 v[112:127], v[2:5], v[164:167], v[112:127]
	ds_read_b128 v[2:5], v6 offset:49152
	s_waitcnt vmcnt(6) lgkmcnt(0)
	v_mfma_f32_32x32x16_bf16 v[128:143], v[2:5], v[168:171], v[128:143]
	ds_read_b128 v[2:5], v6 offset:61440
	v_add_u32_e32 v6, v0, v242
	s_waitcnt lgkmcnt(0)
	v_mfma_f32_32x32x16_bf16 v[112:127], v[2:5], v[168:171], v[112:127]
	ds_read_b128 v[2:5], v6 offset:49152
	s_waitcnt vmcnt(5) lgkmcnt(0)
	v_mfma_f32_32x32x16_bf16 v[128:143], v[2:5], v[172:175], v[128:143]
	ds_read_b128 v[2:5], v6 offset:61440
	s_waitcnt lgkmcnt(0)
	v_mfma_f32_32x32x16_bf16 v[112:127], v[2:5], v[172:175], v[112:127]
	ds_read_b128 v[2:5], v205
	v_add_u32_e32 v10, v0, v243
	ds_read_b128 v[6:9], v10 offset:49152
	ds_read_b128 v[10:13], v10 offset:61440
	s_mov_b32 s11, 0x41000000
	s_waitcnt lgkmcnt(1)
	v_mfma_f32_32x32x16_bf16 v[128:143], v[6:9], v[2:5], v[128:143]
	s_waitcnt lgkmcnt(0)
	v_mfma_f32_32x32x16_bf16 v[112:127], v[10:13], v[2:5], v[112:127]
	ds_read_b128 v[2:5], v205 offset:1024
	v_add_u32_e32 v10, v0, v244
	ds_read_b128 v[6:9], v10 offset:49152
	ds_read_b128 v[10:13], v10 offset:61440
	s_waitcnt lgkmcnt(1)
	v_mfma_f32_32x32x16_bf16 v[128:143], v[6:9], v[2:5], v[128:143]
	s_waitcnt lgkmcnt(0)
	v_mfma_f32_32x32x16_bf16 v[112:127], v[10:13], v[2:5], v[112:127]
	ds_read_b128 v[2:5], v205 offset:2048
	v_add_u32_e32 v10, v0, v245
	ds_read_b128 v[6:9], v10 offset:49152
	ds_read_b128 v[10:13], v10 offset:61440
	v_add_u32_e32 v0, v0, v246
	s_waitcnt lgkmcnt(1)
	v_mfma_f32_32x32x16_bf16 v[128:143], v[6:9], v[2:5], v[128:143]
	s_waitcnt lgkmcnt(0)
	v_mfma_f32_32x32x16_bf16 v[112:127], v[10:13], v[2:5], v[112:127]
	ds_read_b128 v[2:5], v205 offset:3072
	ds_read_b128 v[6:9], v0 offset:49152
	ds_read_b128 v[10:13], v0 offset:61440
	s_waitcnt lgkmcnt(1)
	v_mfma_f32_32x32x16_bf16 v[128:143], v[6:9], v[2:5], v[128:143]
	s_waitcnt lgkmcnt(0)
	v_mfma_f32_32x32x16_bf16 v[112:127], v[10:13], v[2:5], v[112:127]
	s_nop 9
	v_max_f32_e32 v0, v129, v129
	v_max_f32_e32 v2, v128, v128
	v_max_f32_e32 v0, v2, v0
	v_max3_f32 v0, v0, v130, v131
	v_max3_f32 v0, v0, v132, v133
	v_max3_f32 v0, v0, v134, v135
	v_max3_f32 v0, v0, v136, v137
	v_max3_f32 v0, v0, v138, v139
	v_max3_f32 v0, v0, v140, v141
	v_max3_f32 v0, v0, v142, v143
	v_max3_f32 v0, v0, v112, v113
	v_max3_f32 v0, v0, v114, v115
	v_max3_f32 v0, v0, v116, v117
	v_max3_f32 v0, v0, v118, v119
	v_max3_f32 v0, v0, v120, v121
	v_max3_f32 v0, v0, v122, v123
	v_max3_f32 v0, v0, v124, v125
	v_max3_f32 v0, v0, v126, v127
	v_mov_b32_e32 v2, v0
	s_nop 1
	v_permlane32_swap_b32_e32 v0, v2
	v_max_f32_e32 v2, v2, v2
	v_max_f32_e32 v0, v0, v0
	v_max_f32_e32 v2, v0, v2
	v_cmp_ge_f32_e32 vcc, s11, v2
	s_cmp_eq_u64 vcc, exec
	v_mov_b32_e32 v0, 1.0
	s_cbranch_scc0 .LBB0_111

; __device__ __forceinline__ int crow(int r, int hi) { return (r & 3) + 8 * (r >> 2) + 4 * hi; }
; template <int DQK, int LDQ, int LDK, int LDV, int LDO>
; __device__ __forceinline__ void attn_body_s(const bf16* __restrict__ Qb, const bf16* __restrict__ Kh, const bf16* __restrict__ Vh,
;                                             bf16* __restrict__ Ob, int seq, char* lds, int dup) {
;     ...
;         if (__any(al < 1.f)) { if (hi == 0) al_l[r32] = al; asm volatile("s_waitcnt lgkmcnt(0)" ::: "memory");
; #pragma unroll
;             for (int d = 0; d < 4; ++d)
; #pragma unroll
;                 for (int r = 0; r < 16; ++r) o[d][r] *= al_l[crow(r, hi)];
; #pragma unroll
;             for (int r = 0; r < 16; ++r) lsum[r] *= al_l[crow(r, hi)]; }
.LBB0_105:
	v_cmp_gt_f32_e32 vcc, 1.0, v0
	s_cbranch_vccz .LBB0_109
	v_mul_f32_e32 v80, v80, v0
	s_and_saveexec_b64 s[14:15], s[42:43]
	ds_write_b32 v247, v0 offset:128
	s_or_b64 exec, exec, s[14:15]
	s_waitcnt lgkmcnt(0)
	v_add_u32_e32 v0, s5, v204
	ds_read_b128 v[2:5], v0 offset:224
	ds_read_b128 v[6:9], v0 offset:192
	ds_read_b128 v[10:13], v0 offset:160
	ds_read_b128 v[196:199], v0 offset:128
	s_waitcnt lgkmcnt(3)
	v_pk_mul_f32 v[76:77], v[76:77], v[2:3]
	s_waitcnt lgkmcnt(2)
	v_pk_mul_f32 v[72:73], v[72:73], v[6:7]
	s_waitcnt lgkmcnt(1)
	v_pk_mul_f32 v[68:69], v[68:69], v[10:11]
	v_pk_mul_f32 v[78:79], v[78:79], v[4:5]
	v_pk_mul_f32 v[74:75], v[74:75], v[8:9]
	v_pk_mul_f32 v[70:71], v[70:71], v[12:13]
	s_waitcnt lgkmcnt(0)
	v_pk_mul_f32 v[66:67], v[66:67], v[198:199]
	v_pk_mul_f32 v[64:65], v[64:65], v[196:197]
	v_pk_mul_f32 v[60:61], v[60:61], v[2:3]
	v_pk_mul_f32 v[56:57], v[56:57], v[6:7]
	v_pk_mul_f32 v[52:53], v[52:53], v[10:11]
	v_pk_mul_f32 v[62:63], v[62:63], v[4:5]
	v_pk_mul_f32 v[58:59], v[58:59], v[8:9]
	v_pk_mul_f32 v[54:55], v[54:55], v[12:13]
	v_pk_mul_f32 v[50:51], v[50:51], v[198:199]
	v_pk_mul_f32 v[48:49], v[48:49], v[196:197]
	v_pk_mul_f32 v[44:45], v[44:45], v[2:3]
	v_pk_mul_f32 v[40:41], v[40:41], v[6:7]
	v_pk_mul_f32 v[36:37], v[36:37], v[10:11]
	v_pk_mul_f32 v[46:47], v[46:47], v[4:5]
	v_pk_mul_f32 v[42:43], v[42:43], v[8:9]
	v_pk_mul_f32 v[38:39], v[38:39], v[12:13]
	v_pk_mul_f32 v[34:35], v[34:35], v[198:199]
	v_pk_mul_f32 v[32:33], v[32:33], v[196:197]
	v_pk_mul_f32 v[28:29], v[28:29], v[2:3]
	v_pk_mul_f32 v[24:25], v[24:25], v[6:7]
	v_pk_mul_f32 v[20:21], v[20:21], v[10:11]
	v_pk_mul_f32 v[30:31], v[30:31], v[4:5]
	v_pk_mul_f32 v[26:27], v[26:27], v[8:9]
	v_pk_mul_f32 v[22:23], v[22:23], v[12:13]
	v_pk_mul_f32 v[18:19], v[18:19], v[198:199]
	v_pk_mul_f32 v[16:17], v[16:17], v[196:197]
; #define SBAR() __builtin_amdgcn_sched_barrier(0)
; __device__ __forceinline__ void partialSM2(f32x16& p0, f32x16& p1, float& m_hat, f32x16& negm, float& alpha) {
;     ...
;     for (int r = 0; r < 16; ++r) p0[r] = __builtin_amdgcn_exp2f(p0[r]);
; }
; __device__ __forceinline__ void finishSM2(f32x16& p0, f32x16& p1, bf16x8& pa0, bf16x8& pa1, bf16x8& pa2, bf16x8& pa3) {
; #pragma unroll
;     for (int r = 0; r < 16; ++r) p1[r] = __builtin_amdgcn_exp2f(p1[r]);
;     ...
;     PK4(p0, 0, pa0); PK4(p0, 8, pa1); PK4(p1, 0, pa2); PK4(p1, 8, pa3);
; template <int D0> __device__ __forceinline__ void pv_one(f32x16& od, int vb, bf16x8 pa0, bf16x8 pa1, bf16x8 pa2, bf16x8 pa3) {
;     const s16x4 l0 = tr_read<v_rd_off(D0, 0, 0)>(vb), h0 = tr_read<v_rd_off(D0, 0, 1)>(vb), l1 = tr_read<v_rd_off(D0, 1, 0)>(vb), h1 = tr_read<v_rd_off(D0, 1, 1)>(vb);
;     const s16x4 l2 = tr_read<v_rd_off(D0, 2, 0)>(vb), h2 = tr_read<v_rd_off(D0, 2, 1)>(vb), l3 = tr_read<v_rd_off(D0, 3, 0)>(vb), h3 = tr_read<v_rd_off(D0, 3, 1)>(vb);
;     asm volatile("s_waitcnt lgkmcnt(0)" ::: "memory"); SBAR();
;     ...
;     od = __builtin_amdgcn_mfma_f32_32x32x16_bf16(pa0, PK(l0, h0), od, 0, 0, 0);
;     od = __builtin_amdgcn_mfma_f32_32x32x16_bf16(pa1, PK(l1, h1), od, 0, 0, 0);
;     od = __builtin_amdgcn_mfma_f32_32x32x16_bf16(pa2, PK(l2, h2), od, 0, 0, 0);
;     od = __builtin_amdgcn_mfma_f32_32x32x16_bf16(pa3, PK(l3, h3), od, 0, 0, 0);
;     ...
; }
; __device__ __forceinline__ void pv_d0(f32x16* o, int vb, bf16x8 pa0, bf16x8 pa1, bf16x8 pa2, bf16x8 pa3) {
;     pv_one<0>(o[0], vb, pa0, pa1, pa2, pa3); pv_one<1>(o[1], vb, pa0, pa1, pa2, pa3); pv_one<2>(o[2], vb, pa0, pa1, pa2, pa3); pv_one<3>(o[3], vb, pa0, pa1, pa2, pa3);
.LBB0_109:
	v_exp_f32_e32 v2, v129
	v_exp_f32_e32 v3, v130
	v_exp_f32_e32 v4, v131
	v_exp_f32_e32 v5, v132
	v_exp_f32_e32 v6, v133
	v_exp_f32_e32 v7, v134
	v_exp_f32_e32 v8, v135
	v_exp_f32_e32 v9, v136
	v_exp_f32_e32 v10, v137
	v_exp_f32_e32 v11, v138
	v_exp_f32_e32 v12, v139
	v_exp_f32_e32 v13, v140
	v_exp_f32_e32 v112, v112
	v_exp_f32_e32 v113, v113
	v_exp_f32_e32 v114, v114
	v_exp_f32_e32 v115, v115
	v_exp_f32_e32 v0, v128
	v_exp_f32_e32 v14, v141
	v_exp_f32_e32 v15, v142
	v_exp_f32_e32 v128, v143
	v_exp_f32_e32 v116, v116
	v_exp_f32_e32 v117, v117
	v_exp_f32_e32 v118, v118
	v_exp_f32_e32 v119, v119
	v_exp_f32_e32 v120, v120
	v_exp_f32_e32 v121, v121
	v_exp_f32_e32 v122, v122
	v_exp_f32_e32 v123, v123
	v_exp_f32_e32 v124, v124
	v_exp_f32_e32 v125, v125
	v_exp_f32_e32 v126, v126
	v_exp_f32_e32 v127, v127
	v_add_f32_e32 v81, v0, v2
	v_add_f32_e32 v82, v3, v4
	v_add_f32_e32 v83, v5, v6
	v_add_f32_e32 v84, v7, v8
	v_add_f32_e32 v81, v81, v9
	v_add_f32_e32 v82, v82, v10
	v_add_f32_e32 v83, v83, v11
	v_add_f32_e32 v84, v84, v12
	v_add_f32_e32 v81, v81, v13
	v_add_f32_e32 v82, v82, v14
	v_add_f32_e32 v83, v83, v15
	v_add_f32_e32 v84, v84, v128
	v_add_f32_e32 v81, v81, v112
	v_add_f32_e32 v82, v82, v113
	v_add_f32_e32 v83, v83, v114
	v_add_f32_e32 v84, v84, v115
	v_add_f32_e32 v81, v81, v116
	v_add_f32_e32 v82, v82, v117
	v_add_f32_e32 v83, v83, v118
	v_add_f32_e32 v84, v84, v119
	v_add_f32_e32 v81, v81, v120
	v_add_f32_e32 v82, v82, v121
	v_add_f32_e32 v83, v83, v122
	v_add_f32_e32 v84, v84, v123
	v_add_f32_e32 v81, v81, v124
	v_add_f32_e32 v82, v82, v125
	v_add_f32_e32 v83, v83, v126
	v_add_f32_e32 v84, v84, v127
	v_add_f32_e32 v81, v81, v82
	v_add_f32_e32 v83, v83, v84
	v_add_f32_e32 v81, v81, v83
	v_add_f32_e32 v80, v80, v81
	v_cvt_pk_bf16_f32 v2, v0, v2
	v_cvt_pk_bf16_f32 v3, v3, v4
	v_cvt_pk_bf16_f32 v4, v5, v6
	v_cvt_pk_bf16_f32 v5, v7, v8
	v_cvt_pk_bf16_f32 v6, v9, v10
	v_cvt_pk_bf16_f32 v7, v11, v12
	v_cvt_pk_bf16_f32 v8, v13, v14
	v_cvt_pk_bf16_f32 v9, v15, v128
	v_cvt_pk_bf16_f32 v10, v112, v113
	v_cvt_pk_bf16_f32 v11, v114, v115
	v_cvt_pk_bf16_f32 v12, v116, v117
	v_cvt_pk_bf16_f32 v13, v118, v119
	v_cvt_pk_bf16_f32 v112, v120, v121
	v_cvt_pk_bf16_f32 v113, v122, v123
	v_cvt_pk_bf16_f32 v114, v124, v125
	v_cvt_pk_bf16_f32 v115, v126, v127
	s_nop 0
	v_permlane32_swap_b32_e32 v2, v4
	v_permlane32_swap_b32_e32 v3, v5
	v_permlane32_swap_b32_e32 v6, v8
	v_permlane32_swap_b32_e32 v7, v9
	v_permlane32_swap_b32_e32 v10, v12
	v_permlane32_swap_b32_e32 v11, v13
	v_permlane32_swap_b32_e32 v112, v114
	v_permlane32_swap_b32_e32 v113, v115
	v_lshl_add_u32 v0, s7, 14, v248
	s_nop 0
	ds_read_b64_tr_b16 v[116:117], v0 offset:0
	ds_read_b64_tr_b16 v[118:119], v0 offset:0x800
	ds_read_b64_tr_b16 v[120:121], v0 offset:0x1000
	ds_read_b64_tr_b16 v[122:123], v0 offset:0x1800
	ds_read_b64_tr_b16 v[124:125], v0 offset:0x2000
	ds_read_b64_tr_b16 v[126:127], v0 offset:0x2800
	ds_read_b64_tr_b16 v[128:129], v0 offset:0x3000
	ds_read_b64_tr_b16 v[130:131], v0 offset:0x3800
	s_waitcnt lgkmcnt(0)
	s_nop 0
	v_mfma_f32_32x32x16_bf16 v[64:79], v[2:5], v[116:119], v[64:79]
	ds_read_b64_tr_b16 v[116:117], v0 offset:0x200
	ds_read_b64_tr_b16 v[118:119], v0 offset:0xa00
	v_mfma_f32_32x32x16_bf16 v[64:79], v[6:9], v[120:123], v[64:79]
	ds_read_b64_tr_b16 v[120:121], v0 offset:0x1200
	ds_read_b64_tr_b16 v[122:123], v0 offset:0x1a00
	v_mfma_f32_32x32x16_bf16 v[64:79], v[10:13], v[124:127], v[64:79]
	ds_read_b64_tr_b16 v[124:125], v0 offset:0x2200
	ds_read_b64_tr_b16 v[126:127], v0 offset:0x2a00
	v_mfma_f32_32x32x16_bf16 v[64:79], v[112:115], v[128:131], v[64:79]
	ds_read_b64_tr_b16 v[128:129], v0 offset:0x3200
	ds_read_b64_tr_b16 v[130:131], v0 offset:0x3a00
	s_waitcnt lgkmcnt(0)
	v_mfma_f32_32x32x16_bf16 v[48:63], v[2:5], v[116:119], v[48:63]
	ds_read_b64_tr_b16 v[116:117], v0 offset:0x400
	ds_read_b64_tr_b16 v[118:119], v0 offset:0xc00
	v_mfma_f32_32x32x16_bf16 v[48:63], v[6:9], v[120:123], v[48:63]
	ds_read_b64_tr_b16 v[120:121], v0 offset:0x1400
	ds_read_b64_tr_b16 v[122:123], v0 offset:0x1c00
	v_mfma_f32_32x32x16_bf16 v[48:63], v[10:13], v[124:127], v[48:63]
	ds_read_b64_tr_b16 v[124:125], v0 offset:0x2400
	ds_read_b64_tr_b16 v[126:127], v0 offset:0x2c00
	v_mfma_f32_32x32x16_bf16 v[48:63], v[112:115], v[128:131], v[48:63]
	ds_read_b64_tr_b16 v[128:129], v0 offset:0x3400
	ds_read_b64_tr_b16 v[130:131], v0 offset:0x3c00
	s_waitcnt lgkmcnt(0)
	v_mfma_f32_32x32x16_bf16 v[32:47], v[2:5], v[116:119], v[32:47]
	ds_read_b64_tr_b16 v[116:117], v0 offset:0x600
	ds_read_b64_tr_b16 v[118:119], v0 offset:0xe00
	v_mfma_f32_32x32x16_bf16 v[32:47], v[6:9], v[120:123], v[32:47]
	ds_read_b64_tr_b16 v[120:121], v0 offset:0x1600
	ds_read_b64_tr_b16 v[122:123], v0 offset:0x1e00
	v_mfma_f32_32x32x16_bf16 v[32:47], v[10:13], v[124:127], v[32:47]
	ds_read_b64_tr_b16 v[124:125], v0 offset:0x2600
	ds_read_b64_tr_b16 v[126:127], v0 offset:0x2e00
	v_mfma_f32_32x32x16_bf16 v[32:47], v[112:115], v[128:131], v[32:47]
	ds_read_b64_tr_b16 v[128:129], v0 offset:0x3600
	ds_read_b64_tr_b16 v[130:131], v0 offset:0x3e00
	s_waitcnt lgkmcnt(0)
	v_mfma_f32_32x32x16_bf16 v[16:31], v[2:5], v[116:119], v[16:31]
	s_add_i32 s6, s6, 64
	s_cmp_lg_u32 s46, s11
	s_waitcnt lgkmcnt(0)
	s_barrier
	v_mfma_f32_32x32x16_bf16 v[16:31], v[6:9], v[120:123], v[16:31]
	v_mfma_f32_32x32x16_bf16 v[16:31], v[10:13], v[124:127], v[16:31]
	v_mfma_f32_32x32x16_bf16 v[16:31], v[112:115], v[128:131], v[16:31]
	s_cbranch_scc0 .LBB0_113
	s_mov_b32 s14, s11
	s_mov_b32 s11, s7
	s_mov_b32 s7, s9
	s_branch .LBB0_100

; template <int DQK, int LDQ, int LDK, int LDV, int LDO>
; __device__ __forceinline__ void attn_body_s(const bf16* __restrict__ Qb, const bf16* __restrict__ Kh, const bf16* __restrict__ Vh,
;                                             bf16* __restrict__ Ob, int seq, char* lds, int dup) {
;     ...
;     if (late) { pv_d0(o, vb0 + vprev * (int)SHM_V, pa0, pa1, pa2, pa3); }
;     float rli[16];
; #pragma unroll
;     for (int r = 0; r < 16; ++r) rli[r] = __builtin_amdgcn_rcpf(lsum[r]);
;     bf16* Ow = Ob + (long)(wid * QBLK) * LDO;
.LBB0_113:
	v_mov_b32_e32 v81, v80
	s_nop 1
	v_permlane32_swap_b32_e32 v80, v81
	s_nop 0
	v_add_f32_e32 v80, v80, v81
	s_nop 0
	ds_write_b32 v247, v80
	s_waitcnt lgkmcnt(0)
	v_add_u32_e32 v81, s5, v204
	ds_read_b128 v[92:95], v81 offset:96
	ds_read_b128 v[88:91], v81 offset:64
	ds_read_b128 v[84:87], v81 offset:32
	ds_read_b128 v[80:83], v81
	s_waitcnt lgkmcnt(0)
	v_mov_b64_e32 v[248:249], v[218:219]
	v_mov_b32_e32 v218, v224
	v_mov_b32_e32 v219, v221
	v_mov_b32_e32 v221, v222
	v_mov_b32_e32 v222, v220
	v_mov_b32_e32 v220, 0x1b0
	v_bfrev_b32_e32 v224, 0.5

; #define SBAR() __builtin_amdgcn_sched_barrier(0)
; __device__ __forceinline__ void partialSM2(f32x16& p0, f32x16& p1, float& m_hat, f32x16& negm, float& alpha) {
;     float pmax = fmaxf(p0[0], p0[1]);
; #pragma unroll
;     for (int r = 2; r < 16; ++r) pmax = fmaxf(pmax, p0[r]);
; #pragma unroll
;     for (int r = 0; r < 16; ++r) pmax = fmaxf(pmax, p1[r]);
;     { auto rr = __builtin_amdgcn_permlane32_swap(__float_as_uint(pmax), __float_as_uint(pmax), false, false);
;       pmax = fmaxf(__uint_as_float(rr[0]), __uint_as_float(rr[1])); }
;     if (__builtin_expect(__all(pmax <= THR2), 1)) { alpha = 1.f; }
; template <int DQK> __device__ __forceinline__ void qkt(f32x16& p0, f32x16& p1, const char* Ks, const bf16x8* qr, const char* qrl, int r32, int hi, const f32x16& c0) {
;     constexpr int ROWB = Cfg<DQK>::ROWB;
;     p0 = c0; p1 = c0;
; #pragma unroll
;     for (int d0 = 0; d0 < 8; ++d0) { const int cb = (d0 * 16 + hi * 8) * 2;
;         bf16x8 b0 = *reinterpret_cast<const bf16x8*>(Ks + r32 * ROWB + (cb ^ kswz<DQK>(r32)));
;         bf16x8 b1 = *reinterpret_cast<const bf16x8*>(Ks + (32 + r32) * ROWB + (cb ^ kswz<DQK>(r32)));
;         p0 = __builtin_amdgcn_mfma_f32_32x32x16_bf16(b0, qr[d0], p0, 0, 0, 0);
;         p1 = __builtin_amdgcn_mfma_f32_32x32x16_bf16(b1, qr[d0], p1, 0, 0, 0);
;         if constexpr (DQK == 192) { if (d0 == 3 || d0 == 7) SBAR(); } }
.LBB0_118:
	s_mov_b32 s16, s5
	s_mov_b32 s5, s15
	s_and_b32 s15, s7, 0x4000
	v_add_u32_e32 v0, s15, v213
	v_add_u32_e32 v6, v0, v214
	ds_read_b128 v[2:5], v6 offset:49152
	ds_read_b128 v[6:9], v6 offset:57344
	s_waitcnt vmcnt(11) lgkmcnt(1)
	v_mfma_f32_32x32x16_bf16 v[128:143], v[2:5], v[144:147], v[96:111]
	s_mov_b32 s20, 0x41000000
	s_waitcnt lgkmcnt(0)
	v_mfma_f32_32x32x16_bf16 v[112:127], v[6:9], v[144:147], v[96:111]
	v_add_u32_e32 v6, v0, v215
	ds_read_b128 v[2:5], v6 offset:49152
	ds_read_b128 v[6:9], v6 offset:57344
	s_waitcnt vmcnt(10) lgkmcnt(1)
	v_mfma_f32_32x32x16_bf16 v[128:143], v[2:5], v[148:151], v[128:143]
	s_waitcnt lgkmcnt(0)
	v_mfma_f32_32x32x16_bf16 v[112:127], v[6:9], v[148:151], v[112:127]
	v_add_u32_e32 v6, v0, v229
	ds_read_b128 v[2:5], v6 offset:49152
	ds_read_b128 v[6:9], v6 offset:57344
	s_waitcnt vmcnt(9) lgkmcnt(1)
	v_mfma_f32_32x32x16_bf16 v[128:143], v[2:5], v[152:155], v[128:143]
	s_waitcnt lgkmcnt(0)
	v_mfma_f32_32x32x16_bf16 v[112:127], v[6:9], v[152:155], v[112:127]
	v_add_u32_e32 v6, v0, v230
	ds_read_b128 v[2:5], v6 offset:49152
	ds_read_b128 v[6:9], v6 offset:57344
	s_waitcnt vmcnt(8) lgkmcnt(1)
	v_mfma_f32_32x32x16_bf16 v[128:143], v[2:5], v[156:159], v[128:143]
	s_waitcnt lgkmcnt(0)
	v_mfma_f32_32x32x16_bf16 v[112:127], v[6:9], v[156:159], v[112:127]
	v_add_u32_e32 v6, v0, v231
	ds_read_b128 v[2:5], v6 offset:49152
	ds_read_b128 v[6:9], v6 offset:57344
	s_waitcnt vmcnt(7) lgkmcnt(1)
	v_mfma_f32_32x32x16_bf16 v[128:143], v[2:5], v[160:163], v[128:143]
	s_waitcnt lgkmcnt(0)
	v_mfma_f32_32x32x16_bf16 v[112:127], v[6:9], v[160:163], v[112:127]
	v_add_u32_e32 v6, v0, v232
	ds_read_b128 v[2:5], v6 offset:49152
	ds_read_b128 v[6:9], v6 offset:57344
	s_waitcnt vmcnt(6) lgkmcnt(1)
	v_mfma_f32_32x32x16_bf16 v[128:143], v[2:5], v[164:167], v[128:143]
	s_waitcnt lgkmcnt(0)
	v_mfma_f32_32x32x16_bf16 v[112:127], v[6:9], v[164:167], v[112:127]
	v_add_u32_e32 v6, v0, v233
	ds_read_b128 v[2:5], v6 offset:49152
	ds_read_b128 v[6:9], v6 offset:57344
	v_add_u32_e32 v0, v0, v234
	s_waitcnt vmcnt(5) lgkmcnt(1)
	v_mfma_f32_32x32x16_bf16 v[128:143], v[2:5], v[168:171], v[128:143]
	s_waitcnt lgkmcnt(0)
	v_mfma_f32_32x32x16_bf16 v[112:127], v[6:9], v[168:171], v[112:127]
	ds_read_b128 v[2:5], v0 offset:49152
	ds_read_b128 v[6:9], v0 offset:57344
	s_waitcnt vmcnt(4) lgkmcnt(1)
	v_mfma_f32_32x32x16_bf16 v[128:143], v[2:5], v[172:175], v[128:143]
	s_waitcnt lgkmcnt(0)
	v_mfma_f32_32x32x16_bf16 v[112:127], v[6:9], v[172:175], v[112:127]
	s_nop 9
	v_max_f32_e32 v0, v129, v129
	v_max_f32_e32 v2, v128, v128
	v_max_f32_e32 v0, v2, v0
	v_max3_f32 v0, v0, v130, v131
	v_max3_f32 v0, v0, v132, v133
	v_max3_f32 v0, v0, v134, v135
	v_max3_f32 v0, v0, v136, v137
	v_max3_f32 v0, v0, v138, v139
	v_max3_f32 v0, v0, v140, v141
	v_max3_f32 v0, v0, v142, v143
	v_max3_f32 v0, v0, v112, v113
	v_max3_f32 v0, v0, v114, v115
	v_max3_f32 v0, v0, v116, v117
	v_max3_f32 v0, v0, v118, v119
	v_max3_f32 v0, v0, v120, v121
	v_max3_f32 v0, v0, v122, v123
	v_max3_f32 v0, v0, v124, v125
	v_max3_f32 v0, v0, v126, v127
	v_mov_b32_e32 v2, v0
	s_nop 1
	v_permlane32_swap_b32_e32 v0, v2
	v_max_f32_e32 v2, v2, v2
	v_max_f32_e32 v0, v0, v0
	v_max_f32_e32 v2, v0, v2
	v_cmp_ge_f32_e32 vcc, s20, v2
	s_cmp_eq_u64 vcc, exec
	v_mov_b32_e32 v0, 1.0
	s_cbranch_scc0 .LBB0_129

; __device__ __forceinline__ int crow(int r, int hi) { return (r & 3) + 8 * (r >> 2) + 4 * hi; }
; template <int DQK, int LDQ, int LDK, int LDV, int LDO>
; __device__ __forceinline__ void attn_body_s(const bf16* __restrict__ Qb, const bf16* __restrict__ Kh, const bf16* __restrict__ Vh,
;                                             bf16* __restrict__ Ob, int seq, char* lds, int dup) {
;     ...
;         if (__any(al < 1.f)) { if (hi == 0) al_l[r32] = al; asm volatile("s_waitcnt lgkmcnt(0)" ::: "memory");
; #pragma unroll
;             for (int d = 0; d < 4; ++d)
; #pragma unroll
;                 for (int r = 0; r < 16; ++r) o[d][r] *= al_l[crow(r, hi)];
; #pragma unroll
;             for (int r = 0; r < 16; ++r) lsum[r] *= al_l[crow(r, hi)]; }
.LBB0_123:
	v_cmp_gt_f32_e32 vcc, 1.0, v0
	s_cbranch_vccz .LBB0_127
	v_mul_f32_e32 v80, v80, v0
	s_and_saveexec_b64 s[14:15], s[40:41]
	ds_write_b32 v235, v0 offset:128
	s_or_b64 exec, exec, s[14:15]
	s_waitcnt lgkmcnt(0)
	v_add_u32_e32 v0, s6, v206
	ds_read_b128 v[2:5], v0 offset:224
	ds_read_b128 v[6:9], v0 offset:192
	ds_read_b128 v[10:13], v0 offset:160
	ds_read_b128 v[196:199], v0 offset:128
	s_waitcnt lgkmcnt(3)
	v_pk_mul_f32 v[76:77], v[76:77], v[2:3]
	s_waitcnt lgkmcnt(2)
	v_pk_mul_f32 v[72:73], v[72:73], v[6:7]
	s_waitcnt lgkmcnt(1)
	v_pk_mul_f32 v[68:69], v[68:69], v[10:11]
	v_pk_mul_f32 v[78:79], v[78:79], v[4:5]
	v_pk_mul_f32 v[74:75], v[74:75], v[8:9]
	v_pk_mul_f32 v[70:71], v[70:71], v[12:13]
	s_waitcnt lgkmcnt(0)
	v_pk_mul_f32 v[66:67], v[66:67], v[198:199]
	v_pk_mul_f32 v[64:65], v[64:65], v[196:197]
	v_pk_mul_f32 v[60:61], v[60:61], v[2:3]
	v_pk_mul_f32 v[56:57], v[56:57], v[6:7]
	v_pk_mul_f32 v[52:53], v[52:53], v[10:11]
	v_pk_mul_f32 v[62:63], v[62:63], v[4:5]
	v_pk_mul_f32 v[58:59], v[58:59], v[8:9]
	v_pk_mul_f32 v[54:55], v[54:55], v[12:13]
	v_pk_mul_f32 v[50:51], v[50:51], v[198:199]
	v_pk_mul_f32 v[48:49], v[48:49], v[196:197]
	v_pk_mul_f32 v[44:45], v[44:45], v[2:3]
	v_pk_mul_f32 v[40:41], v[40:41], v[6:7]
	v_pk_mul_f32 v[36:37], v[36:37], v[10:11]
	v_pk_mul_f32 v[46:47], v[46:47], v[4:5]
	v_pk_mul_f32 v[42:43], v[42:43], v[8:9]
	v_pk_mul_f32 v[38:39], v[38:39], v[12:13]
	v_pk_mul_f32 v[34:35], v[34:35], v[198:199]
	v_pk_mul_f32 v[32:33], v[32:33], v[196:197]
	v_pk_mul_f32 v[28:29], v[28:29], v[2:3]
	v_pk_mul_f32 v[24:25], v[24:25], v[6:7]
	v_pk_mul_f32 v[20:21], v[20:21], v[10:11]
	v_pk_mul_f32 v[30:31], v[30:31], v[4:5]
	v_pk_mul_f32 v[26:27], v[26:27], v[8:9]
	v_pk_mul_f32 v[22:23], v[22:23], v[12:13]
	v_pk_mul_f32 v[18:19], v[18:19], v[198:199]
	v_pk_mul_f32 v[16:17], v[16:17], v[196:197]
; #define SBAR() __builtin_amdgcn_sched_barrier(0)
; __device__ __forceinline__ void partialSM2(f32x16& p0, f32x16& p1, float& m_hat, f32x16& negm, float& alpha) {
;     ...
;     for (int r = 0; r < 16; ++r) p0[r] = __builtin_amdgcn_exp2f(p0[r]);
; }
; __device__ __forceinline__ void finishSM2(f32x16& p0, f32x16& p1, bf16x8& pa0, bf16x8& pa1, bf16x8& pa2, bf16x8& pa3) {
; #pragma unroll
;     for (int r = 0; r < 16; ++r) p1[r] = __builtin_amdgcn_exp2f(p1[r]);
;     ...
;     PK4(p0, 0, pa0); PK4(p0, 8, pa1); PK4(p1, 0, pa2); PK4(p1, 8, pa3);
; template <int D0> __device__ __forceinline__ void pv_one(f32x16& od, int vb, bf16x8 pa0, bf16x8 pa1, bf16x8 pa2, bf16x8 pa3) {
;     const s16x4 l0 = tr_read<v_rd_off(D0, 0, 0)>(vb), h0 = tr_read<v_rd_off(D0, 0, 1)>(vb), l1 = tr_read<v_rd_off(D0, 1, 0)>(vb), h1 = tr_read<v_rd_off(D0, 1, 1)>(vb);
;     const s16x4 l2 = tr_read<v_rd_off(D0, 2, 0)>(vb), h2 = tr_read<v_rd_off(D0, 2, 1)>(vb), l3 = tr_read<v_rd_off(D0, 3, 0)>(vb), h3 = tr_read<v_rd_off(D0, 3, 1)>(vb);
;     asm volatile("s_waitcnt lgkmcnt(0)" ::: "memory"); SBAR();
;     ...
;     od = __builtin_amdgcn_mfma_f32_32x32x16_bf16(pa0, PK(l0, h0), od, 0, 0, 0);
;     od = __builtin_amdgcn_mfma_f32_32x32x16_bf16(pa1, PK(l1, h1), od, 0, 0, 0);
;     od = __builtin_amdgcn_mfma_f32_32x32x16_bf16(pa2, PK(l2, h2), od, 0, 0, 0);
;     od = __builtin_amdgcn_mfma_f32_32x32x16_bf16(pa3, PK(l3, h3), od, 0, 0, 0);
;     ...
; }
; __device__ __forceinline__ void pv_d0(f32x16* o, int vb, bf16x8 pa0, bf16x8 pa1, bf16x8 pa2, bf16x8 pa3) {
;     pv_one<0>(o[0], vb, pa0, pa1, pa2, pa3); pv_one<1>(o[1], vb, pa0, pa1, pa2, pa3); pv_one<2>(o[2], vb, pa0, pa1, pa2, pa3); pv_one<3>(o[3], vb, pa0, pa1, pa2, pa3);
.LBB0_127:
	v_exp_f32_e32 v2, v129
	v_exp_f32_e32 v3, v130
	v_exp_f32_e32 v4, v131
	v_exp_f32_e32 v5, v132
	v_exp_f32_e32 v6, v133
	v_exp_f32_e32 v7, v134
	v_exp_f32_e32 v8, v135
	v_exp_f32_e32 v9, v136
	v_exp_f32_e32 v10, v137
	v_exp_f32_e32 v11, v138
	v_exp_f32_e32 v12, v139
	v_exp_f32_e32 v13, v140
	v_exp_f32_e32 v112, v112
	v_exp_f32_e32 v113, v113
	v_exp_f32_e32 v114, v114
	v_exp_f32_e32 v115, v115
	v_exp_f32_e32 v0, v128
	v_exp_f32_e32 v14, v141
	v_exp_f32_e32 v15, v142
	v_exp_f32_e32 v128, v143
	v_exp_f32_e32 v116, v116
	v_exp_f32_e32 v117, v117
	v_exp_f32_e32 v118, v118
	v_exp_f32_e32 v119, v119
	v_exp_f32_e32 v120, v120
	v_exp_f32_e32 v121, v121
	v_exp_f32_e32 v122, v122
	v_exp_f32_e32 v123, v123
	v_exp_f32_e32 v124, v124
	v_exp_f32_e32 v125, v125
	v_exp_f32_e32 v126, v126
	v_exp_f32_e32 v127, v127
	v_add_f32_e32 v81, v0, v2
	v_add_f32_e32 v82, v3, v4
	v_add_f32_e32 v83, v5, v6
	v_add_f32_e32 v84, v7, v8
	v_add_f32_e32 v81, v81, v9
	v_add_f32_e32 v82, v82, v10
	v_add_f32_e32 v83, v83, v11
	v_add_f32_e32 v84, v84, v12
	v_add_f32_e32 v81, v81, v13
	v_add_f32_e32 v82, v82, v14
	v_add_f32_e32 v83, v83, v15
	v_add_f32_e32 v84, v84, v128
	v_add_f32_e32 v81, v81, v112
	v_add_f32_e32 v82, v82, v113
	v_add_f32_e32 v83, v83, v114
	v_add_f32_e32 v84, v84, v115
	v_add_f32_e32 v81, v81, v116
	v_add_f32_e32 v82, v82, v117
	v_add_f32_e32 v83, v83, v118
	v_add_f32_e32 v84, v84, v119
	v_add_f32_e32 v81, v81, v120
	v_add_f32_e32 v82, v82, v121
	v_add_f32_e32 v83, v83, v122
	v_add_f32_e32 v84, v84, v123
	v_add_f32_e32 v81, v81, v124
	v_add_f32_e32 v82, v82, v125
	v_add_f32_e32 v83, v83, v126
	v_add_f32_e32 v84, v84, v127
	v_add_f32_e32 v81, v81, v82
	v_add_f32_e32 v83, v83, v84
	v_add_f32_e32 v81, v81, v83
	v_add_f32_e32 v80, v80, v81
	v_cvt_pk_bf16_f32 v2, v0, v2
	v_cvt_pk_bf16_f32 v3, v3, v4
	v_cvt_pk_bf16_f32 v4, v5, v6
	v_cvt_pk_bf16_f32 v5, v7, v8
	v_cvt_pk_bf16_f32 v6, v9, v10
	v_cvt_pk_bf16_f32 v7, v11, v12
	v_cvt_pk_bf16_f32 v8, v13, v14
	v_cvt_pk_bf16_f32 v9, v15, v128
	v_cvt_pk_bf16_f32 v10, v112, v113
	v_cvt_pk_bf16_f32 v11, v114, v115
	v_cvt_pk_bf16_f32 v12, v116, v117
	v_cvt_pk_bf16_f32 v13, v118, v119
	v_cvt_pk_bf16_f32 v112, v120, v121
	v_cvt_pk_bf16_f32 v113, v122, v123
	v_cvt_pk_bf16_f32 v114, v124, v125
	v_cvt_pk_bf16_f32 v115, v126, v127
	s_nop 0
	v_permlane32_swap_b32_e32 v2, v4
	v_permlane32_swap_b32_e32 v3, v5
	v_permlane32_swap_b32_e32 v6, v8
	v_permlane32_swap_b32_e32 v7, v9
	v_permlane32_swap_b32_e32 v10, v12
	v_permlane32_swap_b32_e32 v11, v13
	v_permlane32_swap_b32_e32 v112, v114
	v_permlane32_swap_b32_e32 v113, v115
	v_lshl_add_u32 v0, s11, 14, v236
	s_nop 0
	ds_read_b64_tr_b16 v[116:117], v0 offset:0
	ds_read_b64_tr_b16 v[118:119], v0 offset:0x800
	ds_read_b64_tr_b16 v[120:121], v0 offset:0x1000
	ds_read_b64_tr_b16 v[122:123], v0 offset:0x1800
	ds_read_b64_tr_b16 v[124:125], v0 offset:0x2000
	ds_read_b64_tr_b16 v[126:127], v0 offset:0x2800
	ds_read_b64_tr_b16 v[128:129], v0 offset:0x3000
	ds_read_b64_tr_b16 v[130:131], v0 offset:0x3800
	s_waitcnt lgkmcnt(0)
	s_nop 0
	v_mfma_f32_32x32x16_bf16 v[64:79], v[2:5], v[116:119], v[64:79]
	ds_read_b64_tr_b16 v[116:117], v0 offset:0x200
	ds_read_b64_tr_b16 v[118:119], v0 offset:0xa00
	v_mfma_f32_32x32x16_bf16 v[64:79], v[6:9], v[120:123], v[64:79]
	ds_read_b64_tr_b16 v[120:121], v0 offset:0x1200
	ds_read_b64_tr_b16 v[122:123], v0 offset:0x1a00
	v_mfma_f32_32x32x16_bf16 v[64:79], v[10:13], v[124:127], v[64:79]
	ds_read_b64_tr_b16 v[124:125], v0 offset:0x2200
	ds_read_b64_tr_b16 v[126:127], v0 offset:0x2a00
	v_mfma_f32_32x32x16_bf16 v[64:79], v[112:115], v[128:131], v[64:79]
	ds_read_b64_tr_b16 v[128:129], v0 offset:0x3200
	ds_read_b64_tr_b16 v[130:131], v0 offset:0x3a00
	s_waitcnt lgkmcnt(0)
	v_mfma_f32_32x32x16_bf16 v[48:63], v[2:5], v[116:119], v[48:63]
	ds_read_b64_tr_b16 v[116:117], v0 offset:0x400
	ds_read_b64_tr_b16 v[118:119], v0 offset:0xc00
	v_mfma_f32_32x32x16_bf16 v[48:63], v[6:9], v[120:123], v[48:63]
	ds_read_b64_tr_b16 v[120:121], v0 offset:0x1400
	ds_read_b64_tr_b16 v[122:123], v0 offset:0x1c00
	v_mfma_f32_32x32x16_bf16 v[48:63], v[10:13], v[124:127], v[48:63]
	ds_read_b64_tr_b16 v[124:125], v0 offset:0x2400
	ds_read_b64_tr_b16 v[126:127], v0 offset:0x2c00
	v_mfma_f32_32x32x16_bf16 v[48:63], v[112:115], v[128:131], v[48:63]
	ds_read_b64_tr_b16 v[128:129], v0 offset:0x3400
	ds_read_b64_tr_b16 v[130:131], v0 offset:0x3c00
	s_waitcnt lgkmcnt(0)
	v_mfma_f32_32x32x16_bf16 v[32:47], v[2:5], v[116:119], v[32:47]
	ds_read_b64_tr_b16 v[116:117], v0 offset:0x600
	ds_read_b64_tr_b16 v[118:119], v0 offset:0xe00
	v_mfma_f32_32x32x16_bf16 v[32:47], v[6:9], v[120:123], v[32:47]
	ds_read_b64_tr_b16 v[120:121], v0 offset:0x1600
	ds_read_b64_tr_b16 v[122:123], v0 offset:0x1e00
	v_mfma_f32_32x32x16_bf16 v[32:47], v[10:13], v[124:127], v[32:47]
	ds_read_b64_tr_b16 v[124:125], v0 offset:0x2600
	ds_read_b64_tr_b16 v[126:127], v0 offset:0x2e00
	v_mfma_f32_32x32x16_bf16 v[32:47], v[112:115], v[128:131], v[32:47]
	ds_read_b64_tr_b16 v[128:129], v0 offset:0x3600
	ds_read_b64_tr_b16 v[130:131], v0 offset:0x3e00
	s_waitcnt lgkmcnt(0)
	v_mfma_f32_32x32x16_bf16 v[16:31], v[2:5], v[116:119], v[16:31]
	s_add_i32 s18, s18, 64
	s_addk_i32 s7, 0x4000
	s_cmp_lg_u32 s46, s20
	s_waitcnt lgkmcnt(0)
	s_barrier
	v_mfma_f32_32x32x16_bf16 v[16:31], v[6:9], v[120:123], v[16:31]
	v_mfma_f32_32x32x16_bf16 v[16:31], v[10:13], v[124:127], v[16:31]
	v_mfma_f32_32x32x16_bf16 v[16:31], v[112:115], v[128:131], v[16:31]
	s_cbranch_scc0 .Lattn128_fin
	s_mov_b32 s14, s20
	s_mov_b32 s15, s11
	s_mov_b32 s11, s16
	s_branch .LBB0_118
.Lattn128_fin:
	v_mov_b32_e32 v81, v80
	s_nop 1
	v_permlane32_swap_b32_e32 v80, v81
	s_nop 0
	v_add_f32_e32 v80, v80, v81
	s_nop 0
	ds_write_b32 v235, v80
	s_waitcnt lgkmcnt(0)
	v_add_u32_e32 v81, s6, v206
	ds_read_b128 v[92:95], v81 offset:96
	ds_read_b128 v[88:91], v81 offset:64
	ds_read_b128 v[84:87], v81 offset:32
	ds_read_b128 v[80:83], v81
	s_waitcnt lgkmcnt(0)
	s_branch .LBB0_69

; __device__ __forceinline__ void e2_row(CArgs& a, int l, int r, int lane, int dup, const E2Regs& g) {
;     bf16_t* Q = dup ? (bf16_t*)((float*)a.out + (10u << 20)) + (size_t)r * 768 : (bf16_t*)(a.ws + WS_QB) + (size_t)r * 768;
;     bf16_t* KB = dup ? (bf16_t*)((float*)a.out + (18u << 20)) + (size_t)r * 768 : (bf16_t*)(a.ws + WS_KB) + (size_t)r * 768;
;     const int i = r % TOK; const bool lat = i >= CTXL; const int n = i - CTXL, prow = n >> 6, pcol = n & 63;
;     const int h16 = lane >> 4, li = lane & 15, h8 = (lane >> 3) & 3, li8 = lane & 7;
;     ...
;     { E2_UNPK(g.qn, x); float ss = 0.f;
; #pragma unroll
;       for (int e = 0; e < 8; ++e) ss += x[e] * x[e];
; #pragma unroll
;       for (int m = 1; m < 16; m <<= 1) ss += __shfl_xor(ss, m);
;       const float rs = rsqrtf(ss * (1.f / 128.f) + EPS) * QSCALE_B;
;       const float* gg = a.in[I_BQNN] + l * 128 + 8 * li; const f32x4 ga = *(const f32x4*)gg, gb = *(const f32x4*)(gg + 4);
;       u32x4 o; o.x = cvt_pk_bf16(x[0] * rs * ga.x, x[1] * rs * ga.y); o.y = cvt_pk_bf16(x[2] * rs * ga.z, x[3] * rs * ga.w);
;       o.z = cvt_pk_bf16(x[4] * rs * gb.x, x[5] * rs * gb.y); o.w = cvt_pk_bf16(x[6] * rs * gb.z, x[7] * rs * gb.w);
;       *(u32x4*)(Q + h16 * 192 + 8 * li) = o; }
;     { E2_UNPK(g.qr, x); float ss = 0.f;
; #pragma unroll
;       for (int e = 0; e < 8; ++e) ss += x[e] * x[e];
; #pragma unroll
;       for (int m = 1; m < 8; m <<= 1) ss += __shfl_xor(ss, m);
;       const float rs = rsqrtf(ss * (1.f / 64.f) + EPS) * QSCALE_B;
;       const float* gg = a.in[I_BQRN] + l * 64 + 8 * li8; const f32x4 ga = *(const f32x4*)gg, gb = *(const f32x4*)(gg + 4);
;       float y[8] = {x[0] * rs * ga.x, x[1] * rs * ga.y, x[2] * rs * ga.z, x[3] * rs * ga.w, x[4] * rs * gb.x, x[5] * rs * gb.y, x[6] * rs * gb.z, x[7] * rs * gb.w};
;       if (lat) { const float pos = (float)(li8 < 4 ? prow : pcol); const bool second = ((li8 >> 1) & 1) != 0;
; #pragma unroll
;           for (int e = 0; e < 8; ++e) { const float ang = pos * __builtin_amdgcn_exp2f(-(float)(8 * (li8 & 1) + e) * (13.287712379549449f / 16.f));
;               const float c = __cosf(ang), sn = __sinf(ang), p = __shfl_xor(y[e], 2); y[e] = second ? (p * sn + y[e] * c) : (y[e] * c - p * sn); } }
;       u32x4 o; o.x = cvt_pk_bf16(y[0], y[1]); o.y = cvt_pk_bf16(y[2], y[3]); o.z = cvt_pk_bf16(y[4], y[5]); o.w = cvt_pk_bf16(y[6], y[7]);
.LBB0_166:
	s_movk_i32 s4, 0x4400
	v_cmp_gt_i32_e32 vcc, s4, v202
	s_and_saveexec_b64 s[8:9], vcc
	s_cbranch_execz .LBB0_179
	v_lshlrev_b32_e32 v5, 3, v200
	v_and_b32_e32 v4, 0x78, v5
	v_and_b32_e32 v8, 56, v5
	v_and_b32_e32 v7, 2, v227
	v_and_b32_e32 v5, 8, v5
	v_cmp_eq_u32_e64 s[40:41], 0, v7
	v_cvt_f32_ubyte0_e32 v7, v5
	v_mul_f32_e32 v7, 0xbf549a78, v7
	v_exp_f32_e32 v72, v7
	v_or_b32_e32 v7, 1, v5
	v_cvt_f32_ubyte0_e32 v7, v7
	v_mul_f32_e32 v7, 0xbf549a78, v7
	v_exp_f32_e32 v73, v7
	v_or_b32_e32 v7, 2, v5
	v_cvt_f32_ubyte0_e32 v7, v7
	s_add_u32 s12, s56, 0x20d00000
	s_load_dwordx4 s[44:47], s[0:1], 0x78
	s_load_dwordx2 s[4:5], s[0:1], 0x88
	v_mul_f32_e32 v7, 0xbf549a78, v7
	s_addc_u32 s13, s57, 0
	s_lshl_b32 s6, s34, 7
	v_exp_f32_e32 v74, v7
	v_or_b32_e32 v7, 3, v5
	v_lshrrev_b32_e32 v0, 4, v200
	s_ashr_i32 s7, s6, 31
	v_cvt_f32_ubyte0_e32 v7, v7
	v_mul_u32_u24_e32 v2, 0xc0, v0
	v_lshlrev_b32_e32 v0, 9, v0
	s_lshl_b64 s[6:7], s[6:7], 2
	v_mul_f32_e32 v7, 0xbf549a78, v7
	v_lshl_add_u64 v[10:11], s[56:57], 0, v[0:1]
	v_lshlrev_b32_e32 v0, 1, v4
	s_waitcnt lgkmcnt(0)
	s_add_u32 s14, s44, s6
	v_exp_f32_e32 v75, v7
	v_or_b32_e32 v7, 4, v5
	v_lshl_add_u64 v[10:11], v[10:11], 0, v[0:1]
	s_addc_u32 s15, s45, s7
	v_lshlrev_b32_e32 v0, 2, v4
	v_cvt_f32_ubyte0_e32 v7, v7
	v_lshl_add_u64 v[36:37], s[14:15], 0, v[0:1]
	s_lshl_b32 s14, s34, 6
	v_mul_f32_e32 v7, 0xbf549a78, v7
	s_ashr_i32 s15, s14, 31
	v_exp_f32_e32 v76, v7
	v_or_b32_e32 v7, 5, v5
	v_bfe_u32 v3, v227, 3, 2
	s_lshl_b64 s[14:15], s[14:15], 2
	v_cvt_f32_ubyte0_e32 v7, v7
	v_mul_u32_u24_e32 v6, 0xc0, v3
	s_mov_b64 s[20:21], 0x22700000
	v_and_b32_e32 v3, 7, v227
	s_add_u32 s4, s4, s14
	v_mul_f32_e32 v7, 0xbf549a78, v7
	v_lshl_add_u64 v[34:35], v[10:11], 0, s[20:21]
	s_addc_u32 s5, s5, s15
	v_lshlrev_b32_e32 v10, 5, v3
	v_mov_b32_e32 v11, v1
	v_exp_f32_e32 v77, v7
	v_or_b32_e32 v7, 6, v5
	v_or_b32_e32 v5, 7, v5
	v_lshl_add_u64 v[38:39], s[4:5], 0, v[10:11]
	v_cvt_f32_ubyte0_e32 v5, v5
	s_add_u32 s4, s46, s6
	v_ashrrev_i32_e32 v203, 31, v202
	v_cmp_gt_u32_e64 s[38:39], 4, v3
	v_mul_f32_e32 v5, 0xbf549a78, v5
	s_addc_u32 s5, s47, s7
	v_lshlrev_b64 v[10:11], 13, v[202:203]
	v_lshlrev_b32_e32 v3, 4, v3
	v_exp_f32_e32 v79, v5
	v_lshl_add_u64 v[40:41], s[4:5], 0, v[0:1]
	v_or_b32_e32 v10, v10, v3
	s_mov_b64 s[4:5], 0x18501200
	v_and_b32_e32 v0, 48, v227
	v_lshlrev_b32_e32 v5, 4, v227
	v_lshl_add_u64 v[42:43], v[10:11], 0, s[4:5]
	v_lshlrev_b64 v[10:11], 11, v[202:203]
	v_lshlrev_b32_e32 v0, 5, v0
	v_and_b32_e32 v5, 0xf0, v5
	v_or3_b32 v10, v10, v0, v5
	s_movk_i32 s6, 0x600
	v_cvt_f32_ubyte0_e32 v7, v7
	v_lshl_add_u64 v[44:45], v[10:11], 0, s[20:21]
	v_mad_i64_i32 v[10:11], s[4:5], v202, s6, 0
	v_mul_f32_e32 v7, 0xbf549a78, v7
	v_or_b32_e32 v12, v10, v3
	v_mov_b32_e32 v13, v11
	v_lshlrev_b32_e32 v0, 1, v6
	v_readlane_b32 s4, v255, 34
	v_exp_f32_e32 v78, v7
	v_lshl_add_u64 v[46:47], v[12:13], 0, v[0:1]
	v_or_b32_e32 v10, v10, v5
	v_lshlrev_b32_e32 v12, 1, v2
	v_mov_b32_e32 v13, v1
	v_add_u32_e32 v7, s4, v228
	v_lshl_add_u64 v[48:49], v[10:11], 0, v[12:13]
	v_mad_i64_i32 v[10:11], s[4:5], v7, s6, 0
	v_or_b32_e32 v14, v10, v3
	v_mov_b32_e32 v15, v11
	v_or_b32_e32 v10, v10, v5
	v_cmp_gt_u32_e64 s[42:43], 32, v200
	v_lshl_add_u64 v[50:51], v[14:15], 0, v[0:1]
	v_lshl_add_u64 v[52:53], v[10:11], 0, v[12:13]
	s_mov_b64 s[50:51], 0
	v_lshlrev_b32_e32 v0, 1, v2
	v_lshlrev_b32_e32 v54, 1, v4
	v_lshlrev_b32_e32 v56, 1, v6
	v_lshlrev_b32_e32 v58, 1, v8
	v_mov_b32_e32 v80, v202
	global_load_dwordx4 v[94:97], v[36:37], off
	global_load_dwordx4 v[98:101], v[36:37], off offset:16
	global_load_dwordx4 v[102:105], v[38:39], off
	global_load_dwordx4 v[106:109], v[38:39], off offset:16
	global_load_dwordx4 v[110:113], v[40:41], off
	global_load_dwordx4 v[114:117], v[40:41], off offset:16
	s_waitcnt vmcnt(0)
	s_branch .LBB0_170
.LBB0_168:
	s_or_b64 exec, exec, s[14:15]
	v_and_b32_e32 v21, 0xffff0000, v2
	v_lshlrev_b32_e32 v20, 16, v2
	v_mul_f32_e32 v6, v21, v21
	v_and_b32_e32 v12, 0xffff0000, v3
	v_lshlrev_b32_e32 v13, 16, v3
	v_fmac_f32_e32 v6, v20, v20
	v_pk_mul_f32 v[2:3], v[12:13], v[12:13]
	v_and_b32_e32 v16, 0xffff0000, v4
	v_add_f32_e32 v3, v3, v6
	v_lshlrev_b32_e32 v17, 16, v4
	v_add_f32_e32 v6, v2, v3
	v_pk_mul_f32 v[2:3], v[16:17], v[16:17]
	v_and_b32_e32 v18, 0xffff0000, v5
	v_add_f32_e32 v3, v3, v6
	v_lshlrev_b32_e32 v19, 16, v5
	v_add_f32_e32 v4, v2, v3
	v_pk_mul_f32 v[2:3], v[18:19], v[18:19]
	s_nop 0
	v_add_f32_e32 v3, v3, v4
	v_mov_b64_e32 v[4:5], v[114:115]
	v_mov_b64_e32 v[6:7], v[116:117]
	v_mov_b64_e32 v[8:9], v[110:111]
	v_mov_b64_e32 v[10:11], v[112:113]
	v_add_f32_e32 v2, v2, v3
	ds_bpermute_b32 v3, v55, v2
	s_waitcnt lgkmcnt(0)
	v_add_f32_e32 v2, v2, v3
	ds_bpermute_b32 v3, v57, v2
	s_waitcnt lgkmcnt(0)
	v_add_f32_e32 v2, v2, v3
	ds_bpermute_b32 v3, v59, v2
	s_waitcnt lgkmcnt(0)
	v_add_f32_e32 v2, v2, v3
	ds_bpermute_b32 v3, v81, v2
	s_waitcnt lgkmcnt(0)
	v_add_f32_e32 v2, v2, v3
	v_fmamk_f32 v2, v2, 0x3c000000, v216
	v_cmp_gt_f32_e32 vcc, s26, v2
	v_mul_f32_e32 v3, 0x4b800000, v2
	s_nop 0
	v_cndmask_b32_e32 v2, v2, v3, vcc
	v_rsq_f32_e32 v2, v2
	s_nop 0
	v_mul_f32_e32 v3, 0x45800000, v2
	v_cndmask_b32_e32 v22, v2, v3, vcc
	v_mul_f32_e32 v2, v22, v20
	v_mul_f32_e32 v3, v22, v21
	v_mul_f32_e32 v2, v8, v2
	v_mul_f32_e32 v3, v9, v3
	v_cvt_pk_bf16_f32 v2, v2, v3
	v_mul_f32_e32 v3, v22, v13
	v_mul_f32_e32 v8, v22, v12
	v_mul_f32_e32 v3, v10, v3
	v_mul_f32_e32 v8, v11, v8
	v_cvt_pk_bf16_f32 v3, v3, v8
	v_mul_f32_e32 v8, v22, v17
	v_mul_f32_e32 v4, v4, v8
	v_mul_f32_e32 v8, v22, v16
	v_mul_f32_e32 v5, v5, v8
	v_cvt_pk_bf16_f32 v4, v4, v5
	v_mul_f32_e32 v5, v22, v19
	v_mul_f32_e32 v5, v6, v5
	v_mul_f32_e32 v6, v22, v18
	v_mul_f32_e32 v6, v7, v6
	v_cvt_pk_bf16_f32 v5, v5, v6
	v_add_co_u32_e32 v6, vcc, 0x24900000, v14
	s_nop 1
	v_addc_co_u32_e32 v7, vcc, 0, v15, vcc
	global_store_dwordx4 v[6:7], v[2:5], off
	s_nop 1

; __device__ __forceinline__ void e2_row(CArgs& a, int l, int r, int lane, int dup, const E2Regs& g) {
;     bf16_t* Q = dup ? (bf16_t*)((float*)a.out + (10u << 20)) + (size_t)r * 768 : (bf16_t*)(a.ws + WS_QB) + (size_t)r * 768;
;     bf16_t* KB = dup ? (bf16_t*)((float*)a.out + (18u << 20)) + (size_t)r * 768 : (bf16_t*)(a.ws + WS_KB) + (size_t)r * 768;
;     const int i = r % TOK; const bool lat = i >= CTXL; const int n = i - CTXL, prow = n >> 6, pcol = n & 63;
;     const int h16 = lane >> 4, li = lane & 15, h8 = (lane >> 3) & 3, li8 = lane & 7;
;     ...
;     { E2_UNPK(g.qn, x); float ss = 0.f;
; #pragma unroll
;       for (int e = 0; e < 8; ++e) ss += x[e] * x[e];
; #pragma unroll
;       for (int m = 1; m < 16; m <<= 1) ss += __shfl_xor(ss, m);
;       const float rs = rsqrtf(ss * (1.f / 128.f) + EPS) * QSCALE_B;
;       const float* gg = a.in[I_BQNN] + l * 128 + 8 * li; const f32x4 ga = *(const f32x4*)gg, gb = *(const f32x4*)(gg + 4);
;       u32x4 o; o.x = cvt_pk_bf16(x[0] * rs * ga.x, x[1] * rs * ga.y); o.y = cvt_pk_bf16(x[2] * rs * ga.z, x[3] * rs * ga.w);
;       o.z = cvt_pk_bf16(x[4] * rs * gb.x, x[5] * rs * gb.y); o.w = cvt_pk_bf16(x[6] * rs * gb.z, x[7] * rs * gb.w);
;       *(u32x4*)(Q + h16 * 192 + 8 * li) = o; }
;     { E2_UNPK(g.qr, x); float ss = 0.f;
; #pragma unroll
;       for (int e = 0; e < 8; ++e) ss += x[e] * x[e];
; #pragma unroll
;       for (int m = 1; m < 8; m <<= 1) ss += __shfl_xor(ss, m);
;       const float rs = rsqrtf(ss * (1.f / 64.f) + EPS) * QSCALE_B;
;       const float* gg = a.in[I_BQRN] + l * 64 + 8 * li8; const f32x4 ga = *(const f32x4*)gg, gb = *(const f32x4*)(gg + 4);
;       float y[8] = {x[0] * rs * ga.x, x[1] * rs * ga.y, x[2] * rs * ga.z, x[3] * rs * ga.w, x[4] * rs * gb.x, x[5] * rs * gb.y, x[6] * rs * gb.z, x[7] * rs * gb.w};
;       if (lat) { const float pos = (float)(li8 < 4 ? prow : pcol); const bool second = ((li8 >> 1) & 1) != 0;
; #pragma unroll
;           for (int e = 0; e < 8; ++e) { const float ang = pos * __builtin_amdgcn_exp2f(-(float)(8 * (li8 & 1) + e) * (13.287712379549449f / 16.f));
;               const float c = __cosf(ang), sn = __sinf(ang), p = __shfl_xor(y[e], 2); y[e] = second ? (p * sn + y[e] * c) : (y[e] * c - p * sn); } }
;       u32x4 o; o.x = cvt_pk_bf16(y[0], y[1]); o.y = cvt_pk_bf16(y[2], y[3]); o.z = cvt_pk_bf16(y[4], y[5]); o.w = cvt_pk_bf16(y[6], y[7]);
.LBB0_170:
	v_lshl_add_u64 v[60:61], s[56:57], 0, v[48:49]
	v_add_co_u32_e32 v64, vcc, 0x20d00000, v60
	v_lshl_add_u64 v[62:63], s[56:57], 0, v[46:47]
	s_nop 0
	v_addc_co_u32_e32 v65, vcc, 0, v61, vcc
	global_load_dwordx4 v[30:33], v[64:65], off
	v_add_co_u32_e32 v2, vcc, 0x20d00000, v62
	v_add_u32_e32 v82, s33, v80
	s_nop 0
	v_addc_co_u32_e32 v3, vcc, 0, v63, vcc
	s_movk_i32 s4, 0x4400
	global_load_dwordx4 v[26:29], v[2:3], off offset:256
	v_lshl_add_u64 v[2:3], s[56:57], 0, v[44:45]
	v_cmp_gt_i32_e64 s[44:45], s4, v82
	global_load_dwordx4 v[18:21], v[2:3], off
	v_lshl_add_u64 v[2:3], s[56:57], 0, v[42:43]
	global_load_dwordx4 v[22:25], v[2:3], off
	v_cndmask_b32_e64 v2, v80, v82, s[44:45]
	v_ashrrev_i32_e32 v3, 31, v2
	v_mov_b64_e32 v[4:5], s[12:13]
	s_movk_i32 s4, 0x600
	v_mad_i64_i32 v[4:5], s[4:5], v2, s4, v[4:5]
	v_lshlrev_b64 v[6:7], 11, v[2:3]
	v_lshlrev_b64 v[2:3], 13, v[2:3]
	v_lshl_add_u64 v[8:9], s[56:57], 0, v[2:3]
	v_lshl_add_u64 v[2:3], v[4:5], 0, v[0:1]
	v_mov_b32_e32 v55, v1
	v_lshl_add_u64 v[2:3], v[2:3], 0, v[54:55]
	v_mov_b32_e32 v57, v1
	v_mul_hi_i32 v55, v80, s94
	global_load_dwordx4 v[14:17], v[2:3], off
	v_lshl_add_u64 v[2:3], v[4:5], 0, v[56:57]
	v_lshrrev_b32_e32 v57, 31, v55
	v_ashrrev_i32_e32 v55, 11, v55
	v_add_u32_e32 v55, v55, v57
	v_mul_i32_i24_e32 v55, 0x1100, v55
	v_sub_u32_e32 v83, v80, v55
	v_mov_b32_e32 v59, v1
	v_lshl_add_u64 v[2:3], v[2:3], 0, v[58:59]
	global_load_dwordx4 v[10:13], v[2:3], off offset:256
	v_lshl_add_u64 v[2:3], v[34:35], 0, v[6:7]
	v_lshl_add_u64 v[6:7], v[8:9], 0, v[58:59]
	s_mov_b32 s4, 0x18501000
	v_add_co_u32_e32 v6, vcc, s4, v6
	global_load_dwordx4 v[2:5], v[2:3], off
	s_nop 0
	v_addc_co_u32_e32 v7, vcc, 0, v7, vcc
	global_load_dwordx4 v[6:9], v[6:7], off offset:512
	v_cmp_lt_i32_e32 vcc, s78, v83
	s_waitcnt vmcnt(0)
	v_and_b32_e32 v84, 0xffff0000, v30
	v_lshlrev_b32_e32 v86, 16, v30
	v_mul_f32_e32 v55, v84, v84
	v_and_b32_e32 v70, 0xffff0000, v31
	v_lshlrev_b32_e32 v71, 16, v31
	v_fmac_f32_e32 v55, v86, v86
	v_pk_mul_f32 v[30:31], v[70:71], v[70:71]
	v_and_b32_e32 v68, 0xffff0000, v32
	v_add_f32_e32 v31, v31, v55
	v_lshlrev_b32_e32 v69, 16, v32
	v_add_f32_e32 v55, v30, v31
	v_pk_mul_f32 v[30:31], v[68:69], v[68:69]
	v_and_b32_e32 v66, 0xffff0000, v33
	v_add_f32_e32 v31, v31, v55
	v_lshlrev_b32_e32 v67, 16, v33
	v_add_f32_e32 v32, v30, v31
	v_pk_mul_f32 v[30:31], v[66:67], v[66:67]
	s_nop 0
	v_add_f32_e32 v31, v31, v32
	v_add_f32_e32 v30, v30, v31
	v_and_b32_e32 v31, 64, v223
	v_add_u32_e32 v31, 64, v31
	v_xor_b32_e32 v32, 1, v223
	v_cmp_lt_i32_e64 s[46:47], v32, v31
	s_nop 1
	v_cndmask_b32_e64 v32, v223, v32, s[46:47]
	v_lshlrev_b32_e32 v55, 2, v32
	ds_bpermute_b32 v32, v55, v30
	s_waitcnt lgkmcnt(0)
	v_add_f32_e32 v30, v30, v32
	v_xor_b32_e32 v32, 2, v223
	v_cmp_lt_i32_e64 s[46:47], v32, v31
	s_nop 1
	v_cndmask_b32_e64 v32, v223, v32, s[46:47]
	v_lshlrev_b32_e32 v57, 2, v32
	ds_bpermute_b32 v32, v57, v30
	s_waitcnt lgkmcnt(0)
	v_add_f32_e32 v30, v30, v32
	v_xor_b32_e32 v32, 4, v223
	v_cmp_lt_i32_e64 s[46:47], v32, v31
	s_nop 1
	v_cndmask_b32_e64 v32, v223, v32, s[46:47]
	v_lshlrev_b32_e32 v59, 2, v32
	ds_bpermute_b32 v32, v59, v30
	s_waitcnt lgkmcnt(0)
	v_add_f32_e32 v30, v30, v32
	v_xor_b32_e32 v32, 8, v223
	v_cmp_lt_i32_e64 s[46:47], v32, v31
	s_nop 1
	v_cndmask_b32_e64 v31, v223, v32, s[46:47]
	v_lshlrev_b32_e32 v81, 2, v31
	ds_bpermute_b32 v31, v81, v30
	s_waitcnt lgkmcnt(0)
	v_add_f32_e32 v30, v30, v31
	v_fmamk_f32 v30, v30, 0x3c000000, v216
	v_cmp_gt_f32_e64 s[46:47], s26, v30
	v_mul_f32_e32 v31, 0x4b800000, v30
	s_nop 0
	v_cndmask_b32_e64 v30, v30, v31, s[46:47]
	v_rsq_f32_e32 v30, v30
	s_nop 0
	v_mul_f32_e32 v31, 0x45800000, v30
	v_cndmask_b32_e64 v30, v30, v31, s[46:47]
	v_mul_f32_e32 v85, 0x3dd53b94, v30
	v_mov_b64_e32 v[30:31], v[98:99]
	v_mov_b64_e32 v[32:33], v[100:101]
	v_mov_b64_e32 v[88:89], v[94:95]
	v_mov_b64_e32 v[90:91], v[96:97]
	v_mul_f32_e32 v86, v85, v86
	v_mul_f32_e32 v69, v85, v69
	v_mul_f32_e32 v68, v85, v68
	v_mul_f32_e32 v84, v85, v84
	v_mul_f32_e32 v71, v85, v71
	v_mul_f32_e32 v70, v85, v70
	v_mul_f32_e32 v30, v30, v69
	v_mul_f32_e32 v86, v88, v86
	v_mul_f32_e32 v31, v31, v68
	v_mul_f32_e32 v84, v89, v84
	v_cvt_pk_bf16_f32 v86, v86, v84
	v_mul_f32_e32 v71, v90, v71
	v_mul_f32_e32 v70, v91, v70
	v_cvt_pk_bf16_f32 v87, v71, v70
	v_cvt_pk_bf16_f32 v88, v30, v31
	v_mul_f32_e32 v30, v85, v67
	v_mul_f32_e32 v31, v85, v66
	v_mul_f32_e32 v30, v32, v30
	v_mul_f32_e32 v31, v33, v31
	v_cvt_pk_bf16_f32 v89, v30, v31
	global_store_dwordx4 v[64:65], v[86:89], off
	s_nop 1
	v_mov_b64_e32 v[30:31], v[106:107]
	v_mov_b64_e32 v[32:33], v[108:109]
	s_nop 0
	v_mov_b64_e32 v[64:65], v[102:103]
	v_mov_b64_e32 v[66:67], v[104:105]
	v_lshlrev_b32_e32 v68, 16, v26
	v_and_b32_e32 v69, 0xffff0000, v26
	v_pk_mul_f32 v[70:71], v[68:69], v[68:69]
	v_lshlrev_b32_e32 v84, 16, v27
	v_and_b32_e32 v85, 0xffff0000, v27
	v_pk_mul_f32 v[26:27], v[84:85], v[84:85]
	v_add_f32_e32 v70, v70, v71
	v_lshlrev_b32_e32 v86, 16, v28
	v_and_b32_e32 v87, 0xffff0000, v28
	v_add_f32_e32 v26, v26, v70
	v_pk_mul_f32 v[88:89], v[86:87], v[86:87]
	v_add_f32_e32 v26, v27, v26
	v_lshlrev_b32_e32 v90, 16, v29
	v_and_b32_e32 v91, 0xffff0000, v29
	v_add_f32_e32 v26, v88, v26
	v_pk_mul_f32 v[28:29], v[90:91], v[90:91]
	v_add_f32_e32 v26, v89, v26
	v_add_f32_e32 v26, v28, v26
	v_add_f32_e32 v26, v29, v26
	ds_bpermute_b32 v27, v55, v26
	s_waitcnt lgkmcnt(0)
	v_add_f32_e32 v26, v26, v27
	ds_bpermute_b32 v27, v57, v26
	s_waitcnt lgkmcnt(0)
	v_add_f32_e32 v26, v26, v27
	ds_bpermute_b32 v27, v59, v26
	s_waitcnt lgkmcnt(0)
	v_add_f32_e32 v26, v26, v27
	v_fmamk_f32 v26, v26, 0x3c800000, v216
	v_cmp_gt_f32_e64 s[46:47], s26, v26
	v_mul_f32_e32 v27, 0x4b800000, v26
	s_nop 0
	v_cndmask_b32_e64 v26, v26, v27, s[46:47]
	v_rsq_f32_e32 v26, v26
	s_nop 0
	v_mul_f32_e32 v27, 0x45800000, v26
	v_cndmask_b32_e64 v26, v26, v27, s[46:47]
	v_mul_f32_e32 v70, 0x3dd53b94, v26
	v_pk_mul_f32 v[26:27], v[70:71], v[68:69] op_sel_hi:[0,1]
	v_pk_mul_f32 v[28:29], v[70:71], v[84:85] op_sel_hi:[0,1]
	v_pk_mul_f32 v[26:27], v[64:65], v[26:27]
	v_pk_mul_f32 v[64:65], v[70:71], v[86:87] op_sel_hi:[0,1]
	v_pk_mul_f32 v[30:31], v[30:31], v[64:65]
	v_pk_mul_f32 v[64:65], v[70:71], v[90:91] op_sel_hi:[0,1]
	v_pk_mul_f32 v[28:29], v[66:67], v[28:29]
	v_pk_mul_f32 v[32:33], v[32:33], v[64:65]
	s_and_saveexec_b64 s[20:21], vcc
	s_cbranch_execz .LBB0_172
; __device__ __forceinline__ unsigned cvt_pk_bf16(float lo, float hi) { unsigned r; asm volatile("v_cvt_pk_bf16_f32 %0, %1, %2" : "=v"(r) : "v"(lo), "v"(hi)); return r; }
; #define E2_UNPK(wv_, arr_) float arr_[8] = {bflo(wv_[0]), bfhi(wv_[0]), bflo(wv_[1]), bfhi(wv_[1]), bflo(wv_[2]), bfhi(wv_[2]), bflo(wv_[3]), bfhi(wv_[3])}
; __device__ __forceinline__ void e2_row(CArgs& a, int l, int r, int lane, int dup, const E2Regs& g) {
;     ...
;       if (lat) { const float pos = (float)(li8 < 4 ? prow : pcol); const bool second = ((li8 >> 1) & 1) != 0;
; #pragma unroll
;           for (int e = 0; e < 8; ++e) { const float ang = pos * __builtin_amdgcn_exp2f(-(float)(8 * (li8 & 1) + e) * (13.287712379549449f / 16.f));
;               const float c = __cosf(ang), sn = __sinf(ang), p = __shfl_xor(y[e], 2); y[e] = second ? (p * sn + y[e] * c) : (y[e] * c - p * sn); } }
;       u32x4 o; o.x = cvt_pk_bf16(y[0], y[1]); o.y = cvt_pk_bf16(y[2], y[3]); o.z = cvt_pk_bf16(y[4], y[5]); o.w = cvt_pk_bf16(y[6], y[7]);
;       if (lane < 32) { *(u32x4*)(Q + h8 * 192 + 128 + 8 * li8) = o; *(u32x4*)(KB + h8 * 192 + 128 + 8 * li8) = g.kr; } }
;     { E2_UNPK(g.kn, x); float ss = 0.f;
; #pragma unroll
;       for (int e = 0; e < 8; ++e) ss += x[e] * x[e];
; #pragma unroll
;       for (int m = 1; m < 16; m <<= 1) ss += __shfl_xor(ss, m);
;       const float rs = rsqrtf(ss * (1.f / 128.f) + EPS);
;       const float* gg = a.in[I_BKNN] + l * 128 + 8 * li; const f32x4 ga = *(const f32x4*)gg, gb = *(const f32x4*)(gg + 4);
;       u32x4 o; o.x = cvt_pk_bf16(x[0] * rs * ga.x, x[1] * rs * ga.y); o.y = cvt_pk_bf16(x[2] * rs * ga.z, x[3] * rs * ga.w);
;       o.z = cvt_pk_bf16(x[4] * rs * gb.x, x[5] * rs * gb.y); o.w = cvt_pk_bf16(x[6] * rs * gb.z, x[7] * rs * gb.w);
;       *(u32x4*)(KB + h16 * 192 + 8 * li) = o; }
	v_add_u32_e32 v64, 0xffffff00, v83
	v_lshrrev_b32_e32 v64, 6, v64
	v_and_b32_e32 v65, 63, v83
	v_cndmask_b32_e64 v64, v65, v64, s[38:39]
	v_cvt_f32_u32_e32 v83, v64
	ds_bpermute_b32 v68, v57, v26
	ds_bpermute_b32 v69, v57, v27
	ds_bpermute_b32 v84, v57, v28
	v_mul_f32_e32 v64, v72, v83
	v_mul_f32_e32 v65, 0.15915494, v64
	v_cos_f32_e32 v64, v65
	v_sin_f32_e32 v66, v65
	v_mul_f32_e32 v65, v73, v83
	v_mul_f32_e32 v67, 0.15915494, v65
	v_cos_f32_e32 v65, v67
	v_sin_f32_e32 v67, v67
	ds_bpermute_b32 v85, v57, v29
	ds_bpermute_b32 v88, v57, v30
	ds_bpermute_b32 v89, v57, v31
	s_waitcnt lgkmcnt(4)
	v_pk_mul_f32 v[66:67], v[66:67], v[68:69]
	v_mul_f32_e32 v68, v74, v83
	v_mul_f32_e32 v69, 0.15915494, v68
	v_cos_f32_e32 v68, v69
	v_sin_f32_e32 v70, v69
	v_mul_f32_e32 v69, v75, v83
	v_mul_f32_e32 v71, 0.15915494, v69
	v_cos_f32_e32 v69, v71
	v_sin_f32_e32 v71, v71
	ds_bpermute_b32 v92, v57, v32
	ds_bpermute_b32 v93, v57, v33
	v_cndmask_b32_e64 v67, v67, -v67, s[40:41]
	s_waitcnt lgkmcnt(4)
	v_pk_mul_f32 v[70:71], v[70:71], v[84:85]
	v_mul_f32_e32 v84, v76, v83
	v_mul_f32_e32 v85, 0.15915494, v84
	v_cos_f32_e32 v84, v85
	v_sin_f32_e32 v86, v85
	v_mul_f32_e32 v85, v77, v83
	v_mul_f32_e32 v87, 0.15915494, v85
	v_cos_f32_e32 v85, v87
	v_sin_f32_e32 v87, v87
	v_cndmask_b32_e64 v66, v66, -v66, s[40:41]
	v_cndmask_b32_e64 v71, v71, -v71, s[40:41]
	v_cndmask_b32_e64 v70, v70, -v70, s[40:41]
	s_waitcnt lgkmcnt(2)
	v_pk_mul_f32 v[86:87], v[86:87], v[88:89]
	v_mul_f32_e32 v88, v78, v83
	v_mul_f32_e32 v83, v79, v83
	v_mul_f32_e32 v89, 0.15915494, v88
	v_mul_f32_e32 v83, 0.15915494, v83
	v_sin_f32_e32 v90, v89
	v_sin_f32_e32 v91, v83
	v_cos_f32_e32 v88, v89
	v_cos_f32_e32 v89, v83
	v_cndmask_b32_e64 v87, v87, -v87, s[40:41]
	s_waitcnt lgkmcnt(0)
	v_pk_mul_f32 v[90:91], v[90:91], v[92:93]
	v_cndmask_b32_e64 v86, v86, -v86, s[40:41]
	v_cndmask_b32_e64 v91, v91, -v91, s[40:41]
	v_cndmask_b32_e64 v90, v90, -v90, s[40:41]
	v_pk_fma_f32 v[32:33], v[88:89], v[32:33], v[90:91]
	v_pk_fma_f32 v[30:31], v[84:85], v[30:31], v[86:87]
	v_pk_fma_f32 v[28:29], v[68:69], v[28:29], v[70:71]
	v_pk_fma_f32 v[26:27], v[64:65], v[26:27], v[66:67]
.LBB0_172:
	s_or_b64 exec, exec, s[20:21]
	v_cvt_pk_bf16_f32 v26, v26, v27
	v_cvt_pk_bf16_f32 v27, v28, v29
	v_cvt_pk_bf16_f32 v28, v30, v31
	v_cvt_pk_bf16_f32 v29, v32, v33
	s_and_saveexec_b64 s[14:15], s[42:43]
	s_cbranch_execz .LBB0_174
	s_mov_b64 s[4:5], 0x20d00100
	v_lshl_add_u64 v[30:31], v[62:63], 0, s[4:5]
	global_store_dwordx4 v[30:31], v[26:29], off
	s_nop 1
	s_nop 1
	v_add_co_u32_e32 v26, vcc, 0x24900000, v62
	s_nop 1
	v_addc_co_u32_e32 v27, vcc, 0, v63, vcc
	global_store_dwordx4 v[26:27], v[22:25], off offset:256
	s_nop 1
.LBB0_174:
	s_or_b64 exec, exec, s[14:15]
	v_and_b32_e32 v63, 0xffff0000, v18
	v_lshlrev_b32_e32 v62, 16, v18
	v_mul_f32_e32 v22, v63, v63
	v_and_b32_e32 v28, 0xffff0000, v19
	v_lshlrev_b32_e32 v29, 16, v19
	v_fmac_f32_e32 v22, v62, v62
	v_pk_mul_f32 v[18:19], v[28:29], v[28:29]
	v_and_b32_e32 v30, 0xffff0000, v20
	v_add_f32_e32 v19, v19, v22
	v_lshlrev_b32_e32 v31, 16, v20
	v_add_f32_e32 v22, v18, v19
	v_pk_mul_f32 v[18:19], v[30:31], v[30:31]
	v_and_b32_e32 v32, 0xffff0000, v21
	v_add_f32_e32 v19, v19, v22
	v_lshlrev_b32_e32 v33, 16, v21
	v_add_f32_e32 v20, v18, v19
	v_pk_mul_f32 v[18:19], v[32:33], v[32:33]
	s_nop 0
	v_add_f32_e32 v19, v19, v20
	v_mov_b64_e32 v[20:21], v[114:115]
	v_mov_b64_e32 v[22:23], v[116:117]
	v_mov_b64_e32 v[24:25], v[110:111]
	v_mov_b64_e32 v[26:27], v[112:113]
	v_add_f32_e32 v18, v18, v19
	ds_bpermute_b32 v19, v55, v18
	s_waitcnt lgkmcnt(0)
	v_add_f32_e32 v18, v18, v19
	ds_bpermute_b32 v19, v57, v18
	s_waitcnt lgkmcnt(0)
	v_add_f32_e32 v18, v18, v19
	ds_bpermute_b32 v19, v59, v18
	s_waitcnt lgkmcnt(0)
	v_add_f32_e32 v18, v18, v19
	ds_bpermute_b32 v19, v81, v18
	s_waitcnt lgkmcnt(0)
	v_add_f32_e32 v18, v18, v19
	v_fmamk_f32 v18, v18, 0x3c000000, v216
	v_cmp_gt_f32_e32 vcc, s26, v18
	v_mul_f32_e32 v19, 0x4b800000, v18
	s_nop 0
	v_cndmask_b32_e32 v18, v18, v19, vcc
	v_rsq_f32_e32 v18, v18
	s_nop 0
	v_mul_f32_e32 v19, 0x45800000, v18
	v_cndmask_b32_e32 v64, v18, v19, vcc
	v_mul_f32_e32 v18, v64, v62
	v_mul_f32_e32 v19, v64, v63
	v_mul_f32_e32 v18, v24, v18
	v_mul_f32_e32 v19, v25, v19
	v_cvt_pk_bf16_f32 v18, v18, v19
	v_mul_f32_e32 v19, v64, v29
	v_mul_f32_e32 v24, v64, v28
	v_mul_f32_e32 v19, v26, v19
	v_mul_f32_e32 v24, v27, v24
	v_cvt_pk_bf16_f32 v19, v19, v24
	v_mul_f32_e32 v24, v64, v31
	v_mul_f32_e32 v20, v20, v24
	v_mul_f32_e32 v24, v64, v30
	v_mul_f32_e32 v21, v21, v24
	v_cvt_pk_bf16_f32 v20, v20, v21
	v_mul_f32_e32 v21, v64, v33
	v_mul_f32_e32 v21, v22, v21
	v_mul_f32_e32 v22, v64, v32
	v_mul_f32_e32 v22, v23, v22
	v_cvt_pk_bf16_f32 v21, v21, v22
	v_add_co_u32_e32 v22, vcc, 0x24900000, v60
	s_nop 1
	v_addc_co_u32_e32 v23, vcc, 0, v61, vcc
	global_store_dwordx4 v[22:23], v[18:21], off
	s_nop 1
	s_and_saveexec_b64 s[20:21], s[44:45]
	s_cbranch_execz .LBB0_169
; __device__ __forceinline__ unsigned cvt_pk_bf16(float lo, float hi) { unsigned r; asm volatile("v_cvt_pk_bf16_f32 %0, %1, %2" : "=v"(r) : "v"(lo), "v"(hi)); return r; }
; #define E2_UNPK(wv_, arr_) float arr_[8] = {bflo(wv_[0]), bfhi(wv_[0]), bflo(wv_[1]), bfhi(wv_[1]), bflo(wv_[2]), bfhi(wv_[2]), bflo(wv_[3]), bfhi(wv_[3])}
; __device__ __forceinline__ void e2_row(CArgs& a, int l, int r, int lane, int dup, const E2Regs& g) {
;     ...
;     { E2_UNPK(g.qn, x); float ss = 0.f;
; #pragma unroll
;       for (int e = 0; e < 8; ++e) ss += x[e] * x[e];
; #pragma unroll
;       for (int m = 1; m < 16; m <<= 1) ss += __shfl_xor(ss, m);
;       const float rs = rsqrtf(ss * (1.f / 128.f) + EPS) * QSCALE_B;
;       const float* gg = a.in[I_BQNN] + l * 128 + 8 * li; const f32x4 ga = *(const f32x4*)gg, gb = *(const f32x4*)(gg + 4);
;       u32x4 o; o.x = cvt_pk_bf16(x[0] * rs * ga.x, x[1] * rs * ga.y); o.y = cvt_pk_bf16(x[2] * rs * ga.z, x[3] * rs * ga.w);
;       o.z = cvt_pk_bf16(x[4] * rs * gb.x, x[5] * rs * gb.y); o.w = cvt_pk_bf16(x[6] * rs * gb.z, x[7] * rs * gb.w);
;       *(u32x4*)(Q + h16 * 192 + 8 * li) = o; }
;     { E2_UNPK(g.qr, x); float ss = 0.f;
; #pragma unroll
;       for (int e = 0; e < 8; ++e) ss += x[e] * x[e];
; #pragma unroll
;       for (int m = 1; m < 8; m <<= 1) ss += __shfl_xor(ss, m);
;       const float rs = rsqrtf(ss * (1.f / 64.f) + EPS) * QSCALE_B;
;       const float* gg = a.in[I_BQRN] + l * 64 + 8 * li8; const f32x4 ga = *(const f32x4*)gg, gb = *(const f32x4*)(gg + 4);
;       float y[8] = {x[0] * rs * ga.x, x[1] * rs * ga.y, x[2] * rs * ga.z, x[3] * rs * ga.w, x[4] * rs * gb.x, x[5] * rs * gb.y, x[6] * rs * gb.z, x[7] * rs * gb.w};
;       if (lat) { const float pos = (float)(li8 < 4 ? prow : pcol); const bool second = ((li8 >> 1) & 1) != 0;
; #pragma unroll
;           for (int e = 0; e < 8; ++e) { const float ang = pos * __builtin_amdgcn_exp2f(-(float)(8 * (li8 & 1) + e) * (13.287712379549449f / 16.f));
;               const float c = __cosf(ang), sn = __sinf(ang), p = __shfl_xor(y[e], 2); y[e] = second ? (p * sn + y[e] * c) : (y[e] * c - p * sn); } }
;       u32x4 o; o.x = cvt_pk_bf16(y[0], y[1]); o.y = cvt_pk_bf16(y[2], y[3]); o.z = cvt_pk_bf16(y[4], y[5]); o.w = cvt_pk_bf16(y[6], y[7]);
;       if (lane < 32) { *(u32x4*)(Q + h8 * 192 + 128 + 8 * li8) = o; *(u32x4*)(KB + h8 * 192 + 128 + 8 * li8) = g.kr; } }
	v_mov_b64_e32 v[18:19], v[94:95]
	v_mov_b64_e32 v[20:21], v[96:97]
	v_mov_b64_e32 v[22:23], v[98:99]
	v_mov_b64_e32 v[24:25], v[100:101]
	v_and_b32_e32 v61, 0xffff0000, v14
	v_lshlrev_b32_e32 v60, 16, v14
	v_and_b32_e32 v26, 0xffff0000, v15
	v_lshlrev_b32_e32 v27, 16, v15
	v_mul_f32_e32 v62, v61, v61
	v_pk_mul_f32 v[14:15], v[26:27], v[26:27]
	v_fmac_f32_e32 v62, v60, v60
	v_and_b32_e32 v28, 0xffff0000, v16
	v_lshlrev_b32_e32 v29, 16, v16
	v_add_f32_e32 v15, v15, v62
	v_pk_mul_f32 v[30:31], v[28:29], v[28:29]
	v_add_f32_e32 v14, v14, v15
	v_and_b32_e32 v16, 0xffff0000, v17
	v_lshlrev_b32_e32 v17, 16, v17
	v_add_f32_e32 v14, v31, v14
	v_pk_mul_f32 v[32:33], v[16:17], v[16:17]
	v_add_f32_e32 v14, v30, v14
	v_add_f32_e32 v14, v33, v14
	v_add_f32_e32 v14, v32, v14
	ds_bpermute_b32 v15, v55, v14
	s_mov_b32 s4, 0x20d00000
	s_waitcnt lgkmcnt(0)
	v_add_f32_e32 v14, v14, v15
	ds_bpermute_b32 v15, v57, v14
	s_waitcnt lgkmcnt(0)
	v_add_f32_e32 v14, v14, v15
	ds_bpermute_b32 v15, v59, v14
	s_waitcnt lgkmcnt(0)
	v_add_f32_e32 v30, v14, v15
	ds_bpermute_b32 v31, v81, v30
	v_lshl_add_u64 v[14:15], s[56:57], 0, v[52:53]
	s_waitcnt lgkmcnt(0)
	v_add_f32_e32 v30, v30, v31
	v_fmamk_f32 v30, v30, 0x3c000000, v216
	v_mul_f32_e32 v31, 0x4b800000, v30
	v_cmp_gt_f32_e32 vcc, s26, v30
	s_nop 1
	v_cndmask_b32_e32 v30, v30, v31, vcc
	v_rsq_f32_e32 v32, v30
	v_add_co_u32_e64 v30, s[44:45], s4, v14
	v_mul_f32_e32 v33, 0x45800000, v32
	v_cndmask_b32_e32 v32, v32, v33, vcc
	v_mul_f32_e32 v32, 0x3dd53b94, v32
	v_mul_f32_e32 v33, v32, v60
	v_mul_f32_e32 v60, v32, v61
	v_addc_co_u32_e64 v31, s[44:45], 0, v15, s[44:45]
	v_mul_f32_e32 v27, v32, v27
	v_mul_f32_e32 v26, v32, v26
	v_mul_f32_e32 v29, v32, v29
	v_mul_f32_e32 v28, v32, v28
	v_mul_f32_e32 v17, v32, v17
	v_mul_f32_e32 v16, v32, v16
	v_mul_f32_e32 v18, v18, v33
	v_mul_f32_e32 v19, v19, v60
	v_mul_f32_e32 v20, v20, v27
	v_mul_f32_e32 v21, v21, v26
	v_mul_f32_e32 v22, v22, v29
	v_mul_f32_e32 v23, v23, v28
	v_mul_f32_e32 v24, v24, v17
	v_mul_f32_e32 v25, v25, v16
	v_cvt_pk_bf16_f32 v16, v18, v19
	v_cvt_pk_bf16_f32 v17, v20, v21
	v_cvt_pk_bf16_f32 v18, v22, v23
	v_cvt_pk_bf16_f32 v19, v24, v25
	global_store_dwordx4 v[30:31], v[16:19], off
	s_nop 1
	v_mov_b64_e32 v[16:17], v[102:103]
	v_mov_b64_e32 v[18:19], v[104:105]
	s_nop 0
	v_mov_b64_e32 v[22:23], v[106:107]
	v_mov_b64_e32 v[24:25], v[108:109]
	v_lshlrev_b32_e32 v26, 16, v10
	v_and_b32_e32 v27, 0xffff0000, v10
	v_lshlrev_b32_e32 v10, 16, v11
	v_and_b32_e32 v11, 0xffff0000, v11
	v_pk_mul_f32 v[20:21], v[26:27], v[26:27]
	v_pk_mul_f32 v[30:31], v[10:11], v[10:11]
	v_add_f32_e32 v20, v20, v21
	v_lshlrev_b32_e32 v28, 16, v12
	v_and_b32_e32 v29, 0xffff0000, v12
	v_add_f32_e32 v20, v30, v20
	v_pk_mul_f32 v[32:33], v[28:29], v[28:29]
	v_add_f32_e32 v20, v31, v20
	v_lshlrev_b32_e32 v12, 16, v13
	v_and_b32_e32 v13, 0xffff0000, v13
	v_add_f32_e32 v20, v32, v20
	v_pk_mul_f32 v[60:61], v[12:13], v[12:13]
	v_add_f32_e32 v20, v33, v20
	v_add_f32_e32 v20, v60, v20
	v_add_f32_e32 v20, v61, v20
	ds_bpermute_b32 v21, v55, v20
	v_mul_hi_i32 v30, v82, s94
	v_lshrrev_b32_e32 v31, 31, v30
	v_ashrrev_i32_e32 v30, 11, v30
	v_add_u32_e32 v30, v30, v31
	s_waitcnt lgkmcnt(0)
	v_add_f32_e32 v20, v20, v21
	ds_bpermute_b32 v21, v57, v20
	s_waitcnt lgkmcnt(0)
	v_add_f32_e32 v20, v20, v21
	ds_bpermute_b32 v21, v59, v20
	s_waitcnt lgkmcnt(0)
	v_add_f32_e32 v20, v20, v21
	v_fmamk_f32 v20, v20, 0x3c800000, v216
	v_mul_f32_e32 v21, 0x4b800000, v20
	v_cmp_gt_f32_e32 vcc, s26, v20
	s_nop 1
	v_cndmask_b32_e32 v20, v20, v21, vcc
	v_rsq_f32_e32 v21, v20
	v_mul_i32_i24_e32 v20, 0x1100, v30
	v_sub_u32_e32 v20, v82, v20
	v_cmp_lt_i32_e64 s[44:45], s78, v20
	v_mul_f32_e32 v30, 0x45800000, v21
	v_cndmask_b32_e32 v21, v21, v30, vcc
	v_mul_f32_e32 v30, 0x3dd53b94, v21
	v_pk_mul_f32 v[26:27], v[30:31], v[26:27] op_sel_hi:[0,1]
	v_pk_mul_f32 v[32:33], v[30:31], v[10:11] op_sel_hi:[0,1]
	v_pk_mul_f32 v[28:29], v[30:31], v[28:29] op_sel_hi:[0,1]
	v_pk_mul_f32 v[30:31], v[30:31], v[12:13] op_sel_hi:[0,1]
	v_pk_mul_f32 v[10:11], v[16:17], v[26:27]
	v_pk_mul_f32 v[12:13], v[18:19], v[32:33]
	v_pk_mul_f32 v[16:17], v[22:23], v[28:29]
	v_pk_mul_f32 v[18:19], v[24:25], v[30:31]
	s_and_saveexec_b64 s[22:23], s[44:45]
	s_cbranch_execz .LBB0_177
	v_add_u32_e32 v21, 0xffffff00, v20
	v_lshrrev_b32_e32 v21, 6, v21
	v_and_b32_e32 v20, 63, v20
	v_cndmask_b32_e64 v20, v20, v21, s[38:39]
	v_cvt_f32_u32_e32 v61, v20
	ds_bpermute_b32 v24, v57, v10
	ds_bpermute_b32 v25, v57, v11
	ds_bpermute_b32 v28, v57, v12
	v_mul_f32_e32 v20, v72, v61
	v_mul_f32_e32 v21, 0.15915494, v20
	v_cos_f32_e32 v20, v21
	v_sin_f32_e32 v22, v21
	v_mul_f32_e32 v21, v73, v61
	v_mul_f32_e32 v23, 0.15915494, v21
	v_cos_f32_e32 v21, v23
	v_sin_f32_e32 v23, v23
	ds_bpermute_b32 v29, v57, v13
	ds_bpermute_b32 v32, v57, v16
	ds_bpermute_b32 v33, v57, v17
	s_waitcnt lgkmcnt(4)
	v_pk_mul_f32 v[22:23], v[22:23], v[24:25]
	v_mul_f32_e32 v24, v74, v61
	v_mul_f32_e32 v25, 0.15915494, v24
	v_cos_f32_e32 v24, v25
	v_sin_f32_e32 v26, v25
	v_mul_f32_e32 v25, v75, v61
	v_mul_f32_e32 v27, 0.15915494, v25
	v_cos_f32_e32 v25, v27
	v_sin_f32_e32 v27, v27
	ds_bpermute_b32 v62, v57, v18
	ds_bpermute_b32 v63, v57, v19
	v_cndmask_b32_e64 v23, v23, -v23, s[40:41]
	s_waitcnt lgkmcnt(4)
	v_pk_mul_f32 v[26:27], v[26:27], v[28:29]
	v_mul_f32_e32 v28, v76, v61
	v_mul_f32_e32 v29, 0.15915494, v28
	v_cos_f32_e32 v28, v29
	v_sin_f32_e32 v30, v29
	v_mul_f32_e32 v29, v77, v61
	v_mul_f32_e32 v31, 0.15915494, v29
	v_cos_f32_e32 v29, v31
	v_sin_f32_e32 v31, v31
	v_cndmask_b32_e64 v22, v22, -v22, s[40:41]
	v_cndmask_b32_e64 v27, v27, -v27, s[40:41]
	v_cndmask_b32_e64 v26, v26, -v26, s[40:41]
	s_waitcnt lgkmcnt(2)
	v_pk_mul_f32 v[30:31], v[30:31], v[32:33]
	v_mul_f32_e32 v32, v78, v61
	v_mul_f32_e32 v33, 0.15915494, v32
	v_cos_f32_e32 v32, v33
	v_sin_f32_e32 v60, v33
	v_mul_f32_e32 v33, v79, v61
	v_mul_f32_e32 v61, 0.15915494, v33
	v_cos_f32_e32 v33, v61
	v_sin_f32_e32 v61, v61
	v_cndmask_b32_e64 v31, v31, -v31, s[40:41]
	v_cndmask_b32_e64 v30, v30, -v30, s[40:41]
	v_pk_fma_f32 v[16:17], v[28:29], v[16:17], v[30:31]
	s_waitcnt lgkmcnt(0)
	v_pk_mul_f32 v[60:61], v[60:61], v[62:63]
	v_pk_fma_f32 v[12:13], v[24:25], v[12:13], v[26:27]
	v_cndmask_b32_e64 v61, v61, -v61, s[40:41]
	v_cndmask_b32_e64 v60, v60, -v60, s[40:41]
	v_pk_fma_f32 v[18:19], v[32:33], v[18:19], v[60:61]
	v_pk_fma_f32 v[10:11], v[20:21], v[10:11], v[22:23]
.LBB0_177:
	s_or_b64 exec, exec, s[22:23]
	v_cvt_pk_bf16_f32 v10, v10, v11
	v_cvt_pk_bf16_f32 v11, v12, v13
	v_cvt_pk_bf16_f32 v12, v16, v17
	v_cvt_pk_bf16_f32 v13, v18, v19
	s_and_saveexec_b64 s[14:15], s[42:43]
	s_cbranch_execz .LBB0_168
	v_lshl_add_u64 v[16:17], s[56:57], 0, v[50:51]
	v_add_co_u32_e32 v18, vcc, 0x20d00000, v16
	s_nop 1
	v_addc_co_u32_e32 v19, vcc, 0, v17, vcc
	global_store_dwordx4 v[18:19], v[10:13], off offset:256
	s_nop 1
	s_nop 1
	v_add_co_u32_e32 v10, vcc, 0x24900000, v16
	s_nop 1
	v_addc_co_u32_e32 v11, vcc, 0, v17, vcc
	global_store_dwordx4 v[10:11], v[6:9], off offset:256
	s_nop 1
	s_branch .LBB0_168
